# adds: mLSTM staging threads remapped so 8 lanes read one row's 128 contiguous bytes (K, Q, V rows); segment prefix loads of the output pass batched
# baseline (speedup 1.0000x reference)
; template <bool P2>
; DI void ml_pass(LAS unsigned char* lds, const bf16_t* PROJ, const float* GATES, float* STATE, float* SC, bf16_t* YM,
;                 const float* convw, const float* convb, const float* ogain, int G, int bid) {
;     ...
;         if (P2) {
; #pragma unroll
;             for (int dt = 0; dt < 4; ++dt)
; #pragma unroll
;                 for (int i = 0; i < 16; ++i) Ct[dt][i] = st[((w * 4 + dt) * 16 + i) * 64 + lane];
;             if (tid < 128) ns[tid] = st[32768 + tid];
;             for (int s2 = 0; s2 < sg; ++s2) { const float ml = SC[(uid - sg + s2) * 2], gsg = SC[(uid - sg + s2) * 2 + 1]; m_prev = fmaxf(gsg + m_prev, ml); }
.LBB0_130:
	global_load_dwordx2 v[192:193], v113, s[0:1]
	global_load_dwordx2 v[194:195], v113, s[0:1] offset:8
	global_load_dwordx2 v[196:197], v113, s[0:1] offset:16
	global_load_dwordx2 v[198:199], v113, s[0:1] offset:24
	global_load_dwordx2 v[200:201], v113, s[0:1] offset:32
	global_load_dwordx2 v[202:203], v113, s[0:1] offset:40
	global_load_dwordx2 v[204:205], v113, s[0:1] offset:48
	global_load_dwordx2 v[206:207], v113, s[0:1] offset:56
	global_load_dwordx2 v[208:209], v113, s[0:1] offset:64
	global_load_dwordx2 v[210:211], v113, s[0:1] offset:72
	global_load_dwordx2 v[212:213], v113, s[0:1] offset:80
	global_load_dwordx2 v[214:215], v113, s[0:1] offset:88
	global_load_dwordx2 v[216:217], v113, s[0:1] offset:96
	global_load_dwordx2 v[218:219], v113, s[0:1] offset:104
	global_load_dwordx2 v[220:221], v113, s[0:1] offset:112
	s_waitcnt vmcnt(0)
	v_add_f32_e32 v65, v112, v193
	v_max_f32_e32 v64, v192, v192
	v_max_f32_e32 v112, v65, v64
	s_cmp_eq_u32 s46, 1
	s_cbranch_scc1 .Lsc_done
	v_add_f32_e32 v65, v112, v195
	v_max_f32_e32 v64, v194, v194
	v_max_f32_e32 v112, v65, v64
	s_cmp_eq_u32 s46, 2
	s_cbranch_scc1 .Lsc_done
	v_add_f32_e32 v65, v112, v197
	v_max_f32_e32 v64, v196, v196
	v_max_f32_e32 v112, v65, v64
	s_cmp_eq_u32 s46, 3
	s_cbranch_scc1 .Lsc_done
	v_add_f32_e32 v65, v112, v199
	v_max_f32_e32 v64, v198, v198
	v_max_f32_e32 v112, v65, v64
	s_cmp_eq_u32 s46, 4
	s_cbranch_scc1 .Lsc_done
	v_add_f32_e32 v65, v112, v201
	v_max_f32_e32 v64, v200, v200
	v_max_f32_e32 v112, v65, v64
	s_cmp_eq_u32 s46, 5
	s_cbranch_scc1 .Lsc_done
	v_add_f32_e32 v65, v112, v203
	v_max_f32_e32 v64, v202, v202
	v_max_f32_e32 v112, v65, v64
	s_cmp_eq_u32 s46, 6
	s_cbranch_scc1 .Lsc_done
	v_add_f32_e32 v65, v112, v205
	v_max_f32_e32 v64, v204, v204
	v_max_f32_e32 v112, v65, v64
	s_cmp_eq_u32 s46, 7
	s_cbranch_scc1 .Lsc_done
	v_add_f32_e32 v65, v112, v207
	v_max_f32_e32 v64, v206, v206
	v_max_f32_e32 v112, v65, v64
	s_cmp_eq_u32 s46, 8
	s_cbranch_scc1 .Lsc_done
	v_add_f32_e32 v65, v112, v209
	v_max_f32_e32 v64, v208, v208
	v_max_f32_e32 v112, v65, v64
	s_cmp_eq_u32 s46, 9
	s_cbranch_scc1 .Lsc_done
	v_add_f32_e32 v65, v112, v211
	v_max_f32_e32 v64, v210, v210
	v_max_f32_e32 v112, v65, v64
	s_cmp_eq_u32 s46, 10
	s_cbranch_scc1 .Lsc_done
	v_add_f32_e32 v65, v112, v213
	v_max_f32_e32 v64, v212, v212
	v_max_f32_e32 v112, v65, v64
	s_cmp_eq_u32 s46, 11
	s_cbranch_scc1 .Lsc_done
	v_add_f32_e32 v65, v112, v215
	v_max_f32_e32 v64, v214, v214
	v_max_f32_e32 v112, v65, v64
	s_cmp_eq_u32 s46, 12
	s_cbranch_scc1 .Lsc_done
	v_add_f32_e32 v65, v112, v217
	v_max_f32_e32 v64, v216, v216
	v_max_f32_e32 v112, v65, v64
	s_cmp_eq_u32 s46, 13
	s_cbranch_scc1 .Lsc_done
	v_add_f32_e32 v65, v112, v219
	v_max_f32_e32 v64, v218, v218
	v_max_f32_e32 v112, v65, v64
	s_cmp_eq_u32 s46, 14
	s_cbranch_scc1 .Lsc_done
	v_add_f32_e32 v65, v112, v221
	v_max_f32_e32 v64, v220, v220
	v_max_f32_e32 v112, v65, v64
.Lsc_done:
	s_branch .LBB0_132
.LBB0_131:
	v_mov_b32_e32 v112, 0

; template <bool P2>
; DI void ml_pass(LAS unsigned char* lds, const bf16_t* PROJ, const float* GATES, float* STATE, float* SC, bf16_t* YM,
;                 const float* convw, const float* convb, const float* ogain, int G, int bid) {
;     ...
;             const int sp = tid & 31, pc = tid >> 5;
;             {
;                 u32x4 xr[5];
;                 const bf16_t* kb = PROJ + (row0 + 2 * sp) * 3072 + 512 + 128 * h + 8 * pc;
; #pragma unroll
;                 for (int r = 0; r < 5; ++r) { const int tt = t0 + 2 * sp - 3 + r; xr[r] = (tt >= 0) ? *(const u32x4*)(kb + ((long)r - 3) * 3072) : (u32x4){0u, 0u, 0u, 0u}; }
.LBB0_136:
	v_and_b32_e32 v135, 31, v133
	v_lshrrev_b32_e32 v178, 3, v133
	v_and_b32_e32 v178, 31, v178
	v_lshlrev_b32_e32 v138, 1, v178
	v_or_b32_e32 v66, s60, v138
	v_mov_b64_e32 v[64:65], s[28:29]
	v_mad_u64_u32 v[106:107], s[46:47], v66, s79, v[64:65]
	v_lshrrev_b32_e32 v179, 5, v133
	v_and_b32_e32 v65, 7, v133
	v_and_or_b32 v65, v179, 8, v65
	v_lshlrev_b32_e32 v65, 3, v65
	v_mov_b32_e32 v179, v65
	v_mad_i32_i24 v107, s61, v231, v107
	v_and_b32_e32 v108, -8, v65
	v_lshl_add_u64 v[66:67], v[106:107], 0, s[34:35]
	v_ashrrev_i32_e32 v109, 31, v108
	v_or_b32_e32 v64, s0, v138
	v_lshl_add_u64 v[110:111], v[108:109], 1, v[66:67]
	v_cmp_lt_u32_e64 s[48:49], 2, v64
	v_mov_b32_e32 v66, 0
	v_mov_b32_e32 v70, 0
	v_mov_b32_e32 v71, 0
	v_mov_b32_e32 v72, 0
	v_mov_b32_e32 v73, 0
	s_and_saveexec_b64 s[0:1], s[48:49]
	s_cbranch_execz .LBB0_138
	v_add_co_u32_e32 v68, vcc, 0xffffc000, v110
	s_nop 1
	v_addc_co_u32_e32 v69, vcc, -1, v111, vcc
	global_load_dwordx4 v[70:73], v[68:69], off offset:-1024

; #define LAS __attribute__((address_space(3)))
; DI float silu(float y) { return y * frcp(1.0f + __expf(-y)); }
; DI void conv2(const u32x4 (&x)[5], const LAS float* cw, int dd, float (&y0)[8], float (&y1)[8]) {
;     float xf[5][8];
; #pragma unroll
;     for (int r = 0; r < 5; ++r) { xf[r][0] = bflo(x[r].x); xf[r][1] = bfhi(x[r].x); xf[r][2] = bflo(x[r].y); xf[r][3] = bfhi(x[r].y); xf[r][4] = bflo(x[r].z); xf[r][5] = bfhi(x[r].z); xf[r][6] = bflo(x[r].w); xf[r][7] = bfhi(x[r].w); }
; #pragma unroll
;     for (int j = 0; j < 8; ++j) { const float b = cw[4 * 128 + dd + j]; float a0 = b, a1 = b;
; #pragma unroll
;         for (int tp = 0; tp < 4; ++tp) { const float c = cw[tp * 128 + dd + j]; a0 += xf[tp][j] * c; a1 += xf[tp + 1][j] * c; }
;         y0[j] = silu(a0); y1[j] = silu(a1); }
; template <bool P2>
; DI void ml_pass(LAS unsigned char* lds, const bf16_t* PROJ, const float* GATES, float* STATE, float* SC, bf16_t* YM,
;                 const float* convw, const float* convb, const float* ogain, int G, int bid) {
;     ...
;             const float b_last = __builtin_bit_cast(float, __builtin_amdgcn_readlane(__builtin_bit_cast(int, bcum), 63)), pm63 = __builtin_bit_cast(float, __builtin_amdgcn_readlane(__builtin_bit_cast(int, pm), 63));
;             const float m_new = fmaxf(b_last + m_prev, b_last + pm63);
;             const float decay = __expf(b_last + m_prev - m_new);
;             const float wk = __expf(b_last + gq - m_new);
;             const float mt = fmaxf(bcum + m_prev, bcum + pm);
;             const float inter = __expf(bcum + m_prev - mt);
;             if (w == 0) gs[lane] = gq;
;             const int sp = tid & 31, pc = tid >> 5;
;             {
;                 u32x4 xr[5];
;                 const bf16_t* kb = PROJ + (row0 + 2 * sp) * 3072 + 512 + 128 * h + 8 * pc;
; #pragma unroll
;                 for (int r = 0; r < 5; ++r) { const int tt = t0 + 2 * sp - 3 + r; xr[r] = (tt >= 0) ? *(const u32x4*)(kb + ((long)r - 3) * 3072) : (u32x4){0u, 0u, 0u, 0u}; }
;                 float y0[8], y1[8]; conv2(xr, cw + 640, 8 * pc, y0, y1);
.LBB0_142:
	s_or_b64 exec, exec, s[0:1]
	s_waitcnt lgkmcnt(0)
	global_load_dwordx4 v[86:89], v[110:111], off offset:1024
	v_mov_b32_e32 v79, s78
	v_add_f32_e32 v109, s2, v112
	v_add_f32_e32 v79, s2, v79
	v_max_f32_e32 v132, v109, v79
	v_add_f32_e32 v78, s2, v78
	v_sub_f32_e32 v78, v78, v132
	v_mul_f32_e32 v78, 0x3fb8aa3b, v78
	v_exp_f32_e32 v140, v78
	v_add_co_u32_e32 v78, vcc, s37, v110
	v_lshl_add_u32 v139, v108, 2, 0
	s_nop 0
	v_addc_co_u32_e32 v79, vcc, 0, v111, vcc
	global_load_dwordx4 v[78:81], v[78:79], off offset:3072
	v_add_u32_e32 v102, 0x22000, v139
	ds_read_b128 v[90:93], v102
	ds_read_b128 v[82:85], v102 offset:16
	ds_read_b128 v[94:97], v102 offset:2048
	ds_read_b128 v[98:101], v102 offset:512
	ds_read_b128 v[124:127], v102 offset:1024
	ds_read_b128 v[142:145], v102 offset:1536
	s_waitcnt vmcnt(2)
	v_lshlrev_b32_e32 v104, 16, v70
	v_and_b32_e32 v105, 0xffff0000, v70
	v_lshlrev_b32_e32 v146, 16, v66
	v_and_b32_e32 v147, 0xffff0000, v66
	s_waitcnt lgkmcnt(0)
	v_pk_fma_f32 v[104:105], v[90:91], v[104:105], v[94:95]
	v_lshlrev_b32_e32 v148, 16, v74
	v_and_b32_e32 v149, 0xffff0000, v74
	v_pk_fma_f32 v[104:105], v[98:99], v[146:147], v[104:105]
	v_pk_fma_f32 v[90:91], v[90:91], v[146:147], v[94:95]
	v_pk_fma_f32 v[104:105], v[124:125], v[148:149], v[104:105]
	v_pk_fma_f32 v[90:91], v[98:99], v[148:149], v[90:91]
	v_lshlrev_b32_e32 v70, 16, v71
	v_and_b32_e32 v71, 0xffff0000, v71
	v_lshlrev_b32_e32 v74, 16, v75
	v_and_b32_e32 v75, 0xffff0000, v75
	s_movk_i32 s0, 0xfde4
	v_or_b32_e32 v65, 7, v65
	s_waitcnt vmcnt(1)
	v_lshlrev_b32_e32 v150, 16, v86
	v_and_b32_e32 v151, 0xffff0000, v86
	v_pk_fma_f32 v[104:105], v[142:143], v[150:151], v[104:105]
	v_pk_fma_f32 v[90:91], v[124:125], v[150:151], v[90:91]
	v_mul_f32_e32 v66, 0xbfb8aa3b, v104
	v_exp_f32_e32 v66, v66
	v_lshlrev_b32_e32 v86, 16, v87
	v_and_b32_e32 v87, 0xffff0000, v87
	v_add_f32_e32 v66, 1.0, v66
	v_rcp_f32_e32 v122, v66
	v_mul_f32_e32 v66, 0xbfb8aa3b, v105
	v_exp_f32_e32 v66, v66
	s_nop 0
	v_add_f32_e32 v66, 1.0, v66
	v_rcp_f32_e32 v123, v66
	s_nop 0
	v_pk_mul_f32 v[122:123], v[104:105], v[122:123]
	s_waitcnt vmcnt(0)
	v_lshlrev_b32_e32 v104, 16, v78
	v_and_b32_e32 v105, 0xffff0000, v78
	v_pk_fma_f32 v[90:91], v[142:143], v[104:105], v[90:91]
	s_nop 0
	v_mul_f32_e32 v66, 0xbfb8aa3b, v90
	v_exp_f32_e32 v66, v66
	s_nop 0
	v_add_f32_e32 v66, 1.0, v66
	v_rcp_f32_e32 v94, v66
	v_mul_f32_e32 v66, 0xbfb8aa3b, v91
	v_exp_f32_e32 v66, v66
	s_nop 0
	v_add_f32_e32 v66, 1.0, v66
	v_rcp_f32_e32 v95, v66
	s_nop 0
	v_pk_mul_f32 v[124:125], v[90:91], v[94:95]
	v_lshlrev_b32_e32 v90, 16, v67
	v_and_b32_e32 v91, 0xffff0000, v67
	v_pk_fma_f32 v[66:67], v[92:93], v[70:71], v[96:97]
	s_nop 0
	v_pk_fma_f32 v[66:67], v[100:101], v[90:91], v[66:67]
	s_nop 0
	v_pk_fma_f32 v[66:67], v[126:127], v[74:75], v[66:67]
	s_nop 0
	v_pk_fma_f32 v[66:67], v[144:145], v[86:87], v[66:67]
	s_nop 0
	v_mul_f32_e32 v70, 0xbfb8aa3b, v66
	v_mul_f32_e32 v71, 0xbfb8aa3b, v67
	v_exp_f32_e32 v70, v70
	v_exp_f32_e32 v71, v71
	v_add_f32_e32 v70, 1.0, v70
	v_add_f32_e32 v71, 1.0, v71
	v_rcp_f32_e32 v70, v70
	v_rcp_f32_e32 v71, v71
	s_nop 0
	v_pk_mul_f32 v[66:67], v[66:67], v[70:71]
	v_lshlrev_b32_e32 v70, 16, v79
	v_and_b32_e32 v71, 0xffff0000, v79
	v_pk_fma_f32 v[78:79], v[92:93], v[90:91], v[96:97]
	s_nop 0
	v_pk_fma_f32 v[74:75], v[100:101], v[74:75], v[78:79]
	ds_read_b128 v[90:93], v102 offset:2064
	ds_read_b128 v[94:97], v102 offset:528
	ds_read_b128 v[98:101], v102 offset:1040
	ds_read_b128 v[102:105], v102 offset:1552
	v_pk_fma_f32 v[74:75], v[126:127], v[86:87], v[74:75]
	v_lshlrev_b32_e32 v126, 16, v72
	v_pk_fma_f32 v[70:71], v[144:145], v[70:71], v[74:75]
	v_and_b32_e32 v127, 0xffff0000, v72
	v_mul_f32_e32 v74, 0xbfb8aa3b, v70
	v_mul_f32_e32 v75, 0xbfb8aa3b, v71
	v_exp_f32_e32 v74, v74
	v_exp_f32_e32 v75, v75
	s_waitcnt lgkmcnt(3)
	v_pk_fma_f32 v[126:127], v[82:83], v[126:127], v[90:91]
	v_lshlrev_b32_e32 v78, 16, v76
	v_add_f32_e32 v74, 1.0, v74
	v_add_f32_e32 v75, 1.0, v75
	v_rcp_f32_e32 v74, v74
	v_rcp_f32_e32 v75, v75
	v_and_b32_e32 v79, 0xffff0000, v76
	v_lshlrev_b32_e32 v86, 16, v88
	v_and_b32_e32 v87, 0xffff0000, v88
	v_pk_mul_f32 v[70:71], v[70:71], v[74:75]
	v_lshlrev_b32_e32 v74, 16, v68
	v_and_b32_e32 v75, 0xffff0000, v68
	s_waitcnt lgkmcnt(2)
	v_pk_fma_f32 v[126:127], v[94:95], v[74:75], v[126:127]
	v_pk_fma_f32 v[74:75], v[82:83], v[74:75], v[90:91]
	s_waitcnt lgkmcnt(1)
	v_pk_fma_f32 v[126:127], v[98:99], v[78:79], v[126:127]
	v_pk_fma_f32 v[74:75], v[94:95], v[78:79], v[74:75]
	s_waitcnt lgkmcnt(0)
; #define LAS __attribute__((address_space(3)))
; DI unsigned pk2(float lo, float hi) { f32x2n v = {lo, hi}; bf16x2n b = __builtin_convertvector(v, bf16x2n); return __builtin_bit_cast(unsigned, b); }
; template <bool P2>
; DI void ml_pass(LAS unsigned char* lds, const bf16_t* PROJ, const float* GATES, float* STATE, float* SC, bf16_t* YM,
;                 const float* convw, const float* convb, const float* ogain, int G, int bid) {
;     ...
;                 const bf16_t* kb = PROJ + (row0 + 2 * sp) * 3072 + 512 + 128 * h + 8 * pc;
; #pragma unroll
;                 for (int r = 0; r < 5; ++r) { const int tt = t0 + 2 * sp - 3 + r; xr[r] = (tt >= 0) ? *(const u32x4*)(kb + ((long)r - 3) * 3072) : (u32x4){0u, 0u, 0u, 0u}; }
;                 float y0[8], y1[8]; conv2(xr, cw + 640, 8 * pc, y0, y1);
;                 if (P2) { u32x4 o; o.x = pk2(y0[0], y0[1]); o.y = pk2(y0[2], y0[3]); o.z = pk2(y0[4], y0[5]); o.w = pk2(y0[6], y0[7]); *(LAS u32x4*)(Ks + (2 * sp) * 136 + 8 * pc) = o;
;                     o.x = pk2(y1[0], y1[1]); o.y = pk2(y1[2], y1[3]); o.z = pk2(y1[4], y1[5]); o.w = pk2(y1[6], y1[7]); *(LAS u32x4*)(Ks + (2 * sp + 1) * 136 + 8 * pc) = o; }
;                 const float wk0 = __shfl(wk, 2 * sp), wk1 = __shfl(wk, 2 * sp + 1);
; #pragma unroll
;                 for (int j = 0; j < 8; ++j) Kt32[(8 * pc + j) * 36 + sp] = pk2(y0[j] * wk0, y1[j] * wk1);
;                 asm volatile("" ::: "memory");
;                 if (P2) {
;                     const bf16_t* qb = PROJ + (row0 + 2 * sp) * 3072 + 128 * h + 8 * pc;
; #pragma unroll
;                     for (int r = 0; r < 5; ++r) { const int tt = t0 + 2 * sp - 3 + r; xr[r] = (tt >= 0) ? *(const u32x4*)(qb + ((long)r - 3) * 3072) : (u32x4){0u, 0u, 0u, 0u}; }
	v_pk_fma_f32 v[126:127], v[102:103], v[86:87], v[126:127]
	v_pk_fma_f32 v[74:75], v[98:99], v[86:87], v[74:75]
	v_mul_f32_e32 v68, 0xbfb8aa3b, v126
	v_exp_f32_e32 v68, v68
	v_lshlrev_b32_e32 v72, 16, v73
	v_and_b32_e32 v73, 0xffff0000, v73
	v_pk_fma_f32 v[72:73], v[84:85], v[72:73], v[92:93]
	v_add_f32_e32 v68, 1.0, v68
	v_rcp_f32_e32 v142, v68
	v_mul_f32_e32 v68, 0xbfb8aa3b, v127
	v_exp_f32_e32 v68, v68
	v_lshlrev_b32_e32 v76, 16, v89
	v_add_f32_e32 v68, 1.0, v68
	v_rcp_f32_e32 v143, v68
	s_nop 0
	v_pk_mul_f32 v[142:143], v[126:127], v[142:143]
	v_lshlrev_b32_e32 v126, 16, v80
	v_and_b32_e32 v127, 0xffff0000, v80
	v_pk_fma_f32 v[74:75], v[102:103], v[126:127], v[74:75]
	v_and_b32_e32 v126, 64, v232
	v_mul_f32_e32 v68, 0xbfb8aa3b, v74
	v_exp_f32_e32 v68, v68
	s_nop 0
	v_add_f32_e32 v68, 1.0, v68
	v_rcp_f32_e32 v78, v68
	v_mul_f32_e32 v68, 0xbfb8aa3b, v75
	v_exp_f32_e32 v68, v68
	s_nop 0
	v_add_f32_e32 v68, 1.0, v68
	v_rcp_f32_e32 v79, v68
	v_lshlrev_b32_e32 v68, 16, v69
	v_and_b32_e32 v69, 0xffff0000, v69
	v_pk_fma_f32 v[72:73], v[96:97], v[68:69], v[72:73]
	v_pk_mul_f32 v[78:79], v[74:75], v[78:79]
	v_lshlrev_b32_e32 v74, 16, v77
	v_and_b32_e32 v75, 0xffff0000, v77
	v_and_b32_e32 v77, 0xffff0000, v89
	v_pk_fma_f32 v[72:73], v[100:101], v[74:75], v[72:73]
	v_pk_fma_f32 v[68:69], v[84:85], v[68:69], v[92:93]
	v_pk_fma_f32 v[72:73], v[104:105], v[76:77], v[72:73]
	v_pk_fma_f32 v[68:69], v[96:97], v[74:75], v[68:69]
	v_mul_f32_e32 v80, 0xbfb8aa3b, v72
	v_exp_f32_e32 v80, v80
	v_pk_fma_f32 v[68:69], v[100:101], v[76:77], v[68:69]
	v_lshlrev_b32_e32 v77, 1, v108
	v_cvt_pk_bf16_f32 v74, v142, v143
	v_add_f32_e32 v80, 1.0, v80
	v_rcp_f32_e32 v82, v80
	v_mul_f32_e32 v80, 0xbfb8aa3b, v73
	v_exp_f32_e32 v80, v80
	s_nop 0
	v_add_f32_e32 v80, 1.0, v80
	v_rcp_f32_e32 v83, v80
	v_mul_u32_u24_e32 v80, 0x110, v135
	v_mul_u32_u24_e32 v76, 0x220, v178
	v_pk_mul_f32 v[82:83], v[72:73], v[82:83]
	v_lshlrev_b32_e32 v72, 16, v81
	v_and_b32_e32 v73, 0xffff0000, v81
	v_pk_fma_f32 v[68:69], v[104:105], v[72:73], v[68:69]
	v_cvt_pk_bf16_f32 v75, v82, v83
	v_mul_f32_e32 v72, 0xbfb8aa3b, v68
	v_mul_f32_e32 v73, 0xbfb8aa3b, v69
	v_exp_f32_e32 v72, v72
	v_exp_f32_e32 v73, v73
	v_add_u32_e32 v81, v76, v77
	v_mad_i32_i24 v76, v178, s0, v76
	v_add_f32_e32 v72, 1.0, v72
	v_add_f32_e32 v73, 1.0, v73
	v_rcp_f32_e32 v72, v72
	v_rcp_f32_e32 v73, v73
	s_nop 0
	v_pk_mul_f32 v[68:69], v[68:69], v[72:73]
	v_cvt_pk_bf16_f32 v72, v122, v123
	v_cvt_pk_bf16_f32 v73, v66, v67
	ds_write_b128 v81, v[72:75] offset:17408
	v_or_b32_e32 v81, 1, v138
	v_mul_u32_u24_e32 v84, 0x88, v81
	v_lshlrev_b32_e32 v84, 1, v84
	v_cvt_pk_bf16_f32 v72, v124, v125
	v_cvt_pk_bf16_f32 v73, v70, v71
	v_cvt_pk_bf16_f32 v74, v78, v79
	v_cvt_pk_bf16_f32 v75, v68, v69
	v_add3_u32 v77, 0, v84, v77
	ds_write_b128 v77, v[72:75] offset:17408
	v_or_b32_e32 v72, v126, v138
	v_or_b32_e32 v73, v126, v81
	v_lshlrev_b32_e32 v72, 2, v72
	v_lshlrev_b32_e32 v73, 2, v73
	ds_bpermute_b32 v72, v72, v140
	ds_bpermute_b32 v73, v73, v140
	v_mov_b32_e32 v74, v122
	v_mov_b32_e32 v75, v124
	v_mov_b32_e32 v124, v123
	s_waitcnt lgkmcnt(0)
	v_pk_mul_f32 v[74:75], v[74:75], v[72:73]
	s_nop 0
	v_cvt_pk_bf16_f32 v81, v74, v75
	v_mad_u64_u32 v[74:75], s[0:1], v108, s25, v[76:77]
	v_pk_mul_f32 v[84:85], v[124:125], v[72:73]
	v_add_u32_e32 v86, 0x8800, v74
	v_cvt_pk_bf16_f32 v75, v84, v85
	v_mov_b32_e32 v84, v66
	v_mov_b32_e32 v85, v70
	v_mov_b32_e32 v70, v67
	v_pk_mul_f32 v[84:85], v[84:85], v[72:73]
	v_pk_mul_f32 v[66:67], v[70:71], v[72:73]
	ds_write2_b32 v86, v81, v75 offset1:36
	v_cvt_pk_bf16_f32 v75, v84, v85
	v_cvt_pk_bf16_f32 v66, v66, v67
	ds_write2_b32 v86, v75, v66 offset0:72 offset1:108
	v_mov_b32_e32 v66, v142
	v_mov_b32_e32 v67, v78
	v_pk_mul_f32 v[66:67], v[66:67], v[72:73]
	v_mov_b32_e32 v78, v143
	v_cvt_pk_bf16_f32 v70, v66, v67
	v_pk_mul_f32 v[66:67], v[78:79], v[72:73]
	s_nop 0
	v_cvt_pk_bf16_f32 v66, v66, v67
	ds_write2_b32 v86, v70, v66 offset0:144 offset1:180
	v_mov_b32_e32 v66, v82
	v_mov_b32_e32 v67, v68
	v_pk_mul_f32 v[66:67], v[66:67], v[72:73]
	v_mov_b32_e32 v68, v83
	v_cvt_pk_bf16_f32 v66, v66, v67
	ds_write_b32 v74, v66 offset:35680
	v_pk_mul_f32 v[66:67], v[68:69], v[72:73]
	s_nop 0
	v_cvt_pk_bf16_f32 v68, v66, v67
	v_mad_u64_u32 v[66:67], s[0:1], v65, s25, v[76:77]
	ds_write_b32 v66, v68 offset:34816
	v_mov_b32_e32 v65, 0
	v_mov_b32_e32 v66, 0
	v_mov_b32_e32 v67, 0
	s_and_saveexec_b64 s[0:1], s[48:49]
	s_cbranch_execz .LBB0_144
	v_add_co_u32_e32 v64, vcc, 0xffffc000, v110
	s_nop 1
	v_addc_co_u32_e32 v65, vcc, -1, v111, vcc
	global_load_dwordx4 v[64:67], v[64:65], off offset:-2048

; #define LAS __attribute__((address_space(3)))
; DI unsigned pk2(float lo, float hi) { f32x2n v = {lo, hi}; bf16x2n b = __builtin_convertvector(v, bf16x2n); return __builtin_bit_cast(unsigned, b); }
; DI float silu(float y) { return y * frcp(1.0f + __expf(-y)); }
; DI void conv2(const u32x4 (&x)[5], const LAS float* cw, int dd, float (&y0)[8], float (&y1)[8]) {
;     float xf[5][8];
; #pragma unroll
;     for (int r = 0; r < 5; ++r) { xf[r][0] = bflo(x[r].x); xf[r][1] = bfhi(x[r].x); xf[r][2] = bflo(x[r].y); xf[r][3] = bfhi(x[r].y); xf[r][4] = bflo(x[r].z); xf[r][5] = bfhi(x[r].z); xf[r][6] = bflo(x[r].w); xf[r][7] = bfhi(x[r].w); }
; #pragma unroll
;     for (int j = 0; j < 8; ++j) { const float b = cw[4 * 128 + dd + j]; float a0 = b, a1 = b;
; #pragma unroll
;         for (int tp = 0; tp < 4; ++tp) { const float c = cw[tp * 128 + dd + j]; a0 += xf[tp][j] * c; a1 += xf[tp + 1][j] * c; }
;         y0[j] = silu(a0); y1[j] = silu(a1); }
; template <bool P2>
; DI void ml_pass(LAS unsigned char* lds, const bf16_t* PROJ, const float* GATES, float* STATE, float* SC, bf16_t* YM,
;                 const float* convw, const float* convb, const float* ogain, int G, int bid) {
;     ...
;                     const bf16_t* qb = PROJ + (row0 + 2 * sp) * 3072 + 128 * h + 8 * pc;
; #pragma unroll
;                     for (int r = 0; r < 5; ++r) { const int tt = t0 + 2 * sp - 3 + r; xr[r] = (tt >= 0) ? *(const u32x4*)(qb + ((long)r - 3) * 3072) : (u32x4){0u, 0u, 0u, 0u}; }
;                     conv2(xr, cw, 8 * pc, y0, y1);
;                     const float qs = 0.08838834764831845f;
;                     u32x4 o; o.x = pk2(y0[0] * qs, y0[1] * qs); o.y = pk2(y0[2] * qs, y0[3] * qs); o.z = pk2(y0[4] * qs, y0[5] * qs); o.w = pk2(y0[6] * qs, y0[7] * qs); *(LAS u32x4*)(Qs + (2 * sp) * 136 + 8 * pc) = o;
;                     o.x = pk2(y1[0] * qs, y1[1] * qs); o.y = pk2(y1[2] * qs, y1[3] * qs); o.z = pk2(y1[4] * qs, y1[5] * qs); o.w = pk2(y1[6] * qs, y1[7] * qs); *(LAS u32x4*)(Qs + (2 * sp + 1) * 136 + 8 * pc) = o;
.LBB0_148:
	s_or_b64 exec, exec, s[0:1]
	global_load_dwordx4 v[82:85], v[110:111], off
	v_add_co_u32_e32 v78, vcc, 0x1000, v110
	s_waitcnt vmcnt(1)
	v_lshlrev_b32_e32 v146, 16, v64
	v_addc_co_u32_e32 v79, vcc, 0, v111, vcc
	v_and_b32_e32 v147, 0xffff0000, v64
	v_lshlrev_b32_e32 v152, 16, v65
	v_and_b32_e32 v153, 0xffff0000, v65
	v_lshlrev_b32_e32 v158, 16, v66
	v_and_b32_e32 v159, 0xffff0000, v66
	v_lshlrev_b32_e32 v164, 16, v67
	v_and_b32_e32 v165, 0xffff0000, v67
	global_load_dwordx4 v[64:67], v[78:79], off offset:2048
	v_add_u32_e32 v110, 0x21600, v139
	v_lshlrev_b32_e32 v148, 16, v72
	v_and_b32_e32 v149, 0xffff0000, v72
	v_lshlrev_b32_e32 v150, 16, v68
	v_and_b32_e32 v151, 0xffff0000, v68
	v_lshlrev_b32_e32 v154, 16, v73
	v_and_b32_e32 v155, 0xffff0000, v73
	v_lshlrev_b32_e32 v156, 16, v69
	v_and_b32_e32 v157, 0xffff0000, v69
	v_lshlrev_b32_e32 v160, 16, v74
	v_and_b32_e32 v161, 0xffff0000, v74
	v_lshlrev_b32_e32 v162, 16, v70
	v_and_b32_e32 v163, 0xffff0000, v70
	v_lshlrev_b32_e32 v166, 16, v75
	v_and_b32_e32 v167, 0xffff0000, v75
	v_lshlrev_b32_e32 v168, 16, v71
	v_and_b32_e32 v169, 0xffff0000, v71
	ds_read_b128 v[68:71], v110
	ds_read_b128 v[72:75], v110 offset:16
	ds_read_b128 v[86:89], v110 offset:2048
	ds_read_b128 v[90:93], v110 offset:2064
	ds_read_b128 v[94:97], v110 offset:512
	ds_read_b128 v[98:101], v110 offset:528
	ds_read_b128 v[102:105], v110 offset:1024
	ds_read_b128 v[122:125], v110 offset:1040
	ds_read_b128 v[138:141], v110 offset:1536
	ds_read_b128 v[142:145], v110 offset:1552
	s_waitcnt lgkmcnt(7)
	v_pk_fma_f32 v[78:79], v[68:69], v[146:147], v[86:87]
	v_pk_fma_f32 v[110:111], v[70:71], v[152:153], v[88:89]
	s_waitcnt lgkmcnt(5)
	v_pk_fma_f32 v[78:79], v[94:95], v[148:149], v[78:79]
	v_pk_fma_f32 v[146:147], v[72:73], v[158:159], v[90:91]
	v_pk_fma_f32 v[110:111], v[96:97], v[154:155], v[110:111]
	s_waitcnt lgkmcnt(3)
	v_pk_fma_f32 v[78:79], v[102:103], v[150:151], v[78:79]
	v_pk_fma_f32 v[152:153], v[74:75], v[164:165], v[92:93]
	v_pk_fma_f32 v[146:147], v[98:99], v[160:161], v[146:147]
	v_pk_fma_f32 v[110:111], v[104:105], v[156:157], v[110:111]
	s_waitcnt lgkmcnt(2)
	v_pk_fma_f32 v[146:147], v[122:123], v[162:163], v[146:147]
	v_pk_fma_f32 v[152:153], v[100:101], v[166:167], v[152:153]
	v_pk_fma_f32 v[68:69], v[68:69], v[148:149], v[86:87]
	s_movk_i32 s0, 0x21c
	v_pk_fma_f32 v[68:69], v[94:95], v[150:151], v[68:69]
	v_mad_u32_u24 v76, v178, s0, v76
	v_pk_fma_f32 v[70:71], v[70:71], v[154:155], v[88:89]
	v_lshl_add_u32 v108, v108, 1, v76
	v_pk_fma_f32 v[70:71], v[96:97], v[156:157], v[70:71]
	v_pk_fma_f32 v[72:73], v[72:73], v[160:161], v[90:91]
	v_mul_i32_i24_e32 v81, 0xfffffde4, v178
	v_pk_fma_f32 v[72:73], v[98:99], v[162:163], v[72:73]
	s_lshl_b32 s46, s75, 1
	s_mov_b32 s47, s35
	s_mov_b32 s2, 0
	s_mov_b64 s[48:49], -1
	s_waitcnt vmcnt(1)
	v_lshlrev_b32_e32 v158, 16, v82
	v_and_b32_e32 v159, 0xffff0000, v82
	v_lshlrev_b32_e32 v164, 16, v83
	v_and_b32_e32 v165, 0xffff0000, v83
	s_waitcnt lgkmcnt(1)
	v_pk_fma_f32 v[78:79], v[138:139], v[158:159], v[78:79]
	v_lshlrev_b32_e32 v170, 16, v84
	v_and_b32_e32 v171, 0xffff0000, v84
	v_pk_fma_f32 v[82:83], v[140:141], v[164:165], v[110:111]
	v_mul_f32_e32 v110, 0xbfb8aa3b, v78
	v_mul_f32_e32 v111, 0xbfb8aa3b, v79
	v_lshlrev_b32_e32 v172, 16, v85
	v_and_b32_e32 v173, 0xffff0000, v85
	s_waitcnt lgkmcnt(0)
	v_pk_fma_f32 v[84:85], v[142:143], v[170:171], v[146:147]
	v_mul_f32_e32 v127, 0xbfb8aa3b, v82
	v_mul_f32_e32 v146, 0xbfb8aa3b, v83
	v_exp_f32_e32 v110, v110
	v_exp_f32_e32 v111, v111
	v_mul_f32_e32 v147, 0xbfb8aa3b, v84
	v_exp_f32_e32 v127, v127
	v_exp_f32_e32 v146, v146
	v_exp_f32_e32 v147, v147
	v_add_f32_e32 v110, 1.0, v110
	v_add_f32_e32 v111, 1.0, v111
	v_add_f32_e32 v127, 1.0, v127
	v_add_f32_e32 v175, 1.0, v146
	v_rcp_f32_e32 v110, v110
	v_rcp_f32_e32 v111, v111
	v_add_f32_e32 v176, 1.0, v147
	v_rcp_f32_e32 v146, v127
	v_rcp_f32_e32 v147, v175
	v_pk_mul_f32 v[78:79], v[78:79], v[110:111]
	v_mul_f32_e32 v174, 0xbfb8aa3b, v85
	v_pk_mul_f32 v[78:79], v[78:79], s[36:37] op_sel_hi:[1,0]
	v_pk_mul_f32 v[82:83], v[82:83], v[146:147]
	v_exp_f32_e32 v174, v174
	v_pk_mul_f32 v[110:111], v[82:83], s[36:37] op_sel_hi:[1,0]
	v_cvt_pk_bf16_f32 v82, v78, v79
	v_pk_fma_f32 v[78:79], v[124:125], v[168:169], v[152:153]
	v_cvt_pk_bf16_f32 v83, v110, v111
	v_pk_fma_f32 v[78:79], v[144:145], v[172:173], v[78:79]
	v_add_f32_e32 v127, 1.0, v174
	v_mul_f32_e32 v110, 0xbfb8aa3b, v78
	v_mul_f32_e32 v111, 0xbfb8aa3b, v79
	v_exp_f32_e32 v110, v110
	v_exp_f32_e32 v111, v111
	v_rcp_f32_e32 v174, v176
	v_rcp_f32_e32 v175, v127
	v_add_f32_e32 v110, 1.0, v110
	v_add_f32_e32 v111, 1.0, v111
	v_rcp_f32_e32 v110, v110
	v_rcp_f32_e32 v111, v111
	v_pk_mul_f32 v[84:85], v[84:85], v[174:175]
	v_pk_fma_f32 v[68:69], v[102:103], v[158:159], v[68:69]
	v_pk_mul_f32 v[84:85], v[84:85], s[36:37] op_sel_hi:[1,0]
	v_pk_mul_f32 v[78:79], v[78:79], v[110:111]
	v_cvt_pk_bf16_f32 v84, v84, v85
	v_pk_mul_f32 v[78:79], v[78:79], s[36:37] op_sel_hi:[1,0]
	v_pk_fma_f32 v[70:71], v[104:105], v[164:165], v[70:71]
	v_cvt_pk_bf16_f32 v85, v78, v79
	s_waitcnt vmcnt(0)
; #define LAS __attribute__((address_space(3)))
; DI unsigned pk2(float lo, float hi) { f32x2n v = {lo, hi}; bf16x2n b = __builtin_convertvector(v, bf16x2n); return __builtin_bit_cast(unsigned, b); }
; DI float silu(float y) { return y * frcp(1.0f + __expf(-y)); }
; DI void conv2(const u32x4 (&x)[5], const LAS float* cw, int dd, float (&y0)[8], float (&y1)[8]) {
;     float xf[5][8];
; #pragma unroll
;     for (int r = 0; r < 5; ++r) { xf[r][0] = bflo(x[r].x); xf[r][1] = bfhi(x[r].x); xf[r][2] = bflo(x[r].y); xf[r][3] = bfhi(x[r].y); xf[r][4] = bflo(x[r].z); xf[r][5] = bfhi(x[r].z); xf[r][6] = bflo(x[r].w); xf[r][7] = bfhi(x[r].w); }
; #pragma unroll
;     for (int j = 0; j < 8; ++j) { const float b = cw[4 * 128 + dd + j]; float a0 = b, a1 = b;
; #pragma unroll
;         for (int tp = 0; tp < 4; ++tp) { const float c = cw[tp * 128 + dd + j]; a0 += xf[tp][j] * c; a1 += xf[tp + 1][j] * c; }
;         y0[j] = silu(a0); y1[j] = silu(a1); }
; template <bool P2>
; DI void ml_pass(LAS unsigned char* lds, const bf16_t* PROJ, const float* GATES, float* STATE, float* SC, bf16_t* YM,
;                 const float* convw, const float* convb, const float* ogain, int G, int bid) {
;     ...
;                     u32x4 o; o.x = pk2(y0[0] * qs, y0[1] * qs); o.y = pk2(y0[2] * qs, y0[3] * qs); o.z = pk2(y0[4] * qs, y0[5] * qs); o.w = pk2(y0[6] * qs, y0[7] * qs); *(LAS u32x4*)(Qs + (2 * sp) * 136 + 8 * pc) = o;
;                     o.x = pk2(y1[0] * qs, y1[1] * qs); o.y = pk2(y1[2] * qs, y1[3] * qs); o.z = pk2(y1[4] * qs, y1[5] * qs); o.w = pk2(y1[6] * qs, y1[7] * qs); *(LAS u32x4*)(Qs + (2 * sp + 1) * 136 + 8 * pc) = o;
;                 }
;             }
;             asm volatile("" ::: "memory");
; #pragma unroll 1
;             for (int it = 0; it < 2; ++it) { const int idx = tid + 512 * it, sp2 = idx & 31, pc2 = idx >> 5;
;                 const bf16_t* vb = PROJ + (row0 + 2 * sp2) * 3072 + 1024 + 256 * h + 8 * pc2;
	v_lshlrev_b32_e32 v78, 16, v64
	v_and_b32_e32 v79, 0xffff0000, v64
	v_pk_fma_f32 v[68:69], v[138:139], v[78:79], v[68:69]
	ds_write_b128 v108, v[82:85]
	v_mul_f32_e32 v78, 0xbfb8aa3b, v69
	v_exp_f32_e32 v78, v78
	v_and_b32_e32 v79, 0xffff0000, v65
	v_mul_f32_e32 v64, 0xbfb8aa3b, v68
	v_exp_f32_e32 v64, v64
	v_add_f32_e32 v82, 1.0, v78
	v_lshlrev_b32_e32 v78, 16, v65
	v_pk_fma_f32 v[70:71], v[140:141], v[78:79], v[70:71]
	v_add_f32_e32 v64, 1.0, v64
	v_mul_f32_e32 v65, 0xbfb8aa3b, v70
	v_exp_f32_e32 v78, v65
	v_mul_f32_e32 v65, 0xbfb8aa3b, v71
	v_exp_f32_e32 v79, v65
	v_rcp_f32_e32 v64, v64
	v_add_f32_e32 v78, 1.0, v78
	v_rcp_f32_e32 v65, v82
	v_add_f32_e32 v79, 1.0, v79
	v_rcp_f32_e32 v78, v78
	v_rcp_f32_e32 v79, v79
	v_pk_mul_f32 v[64:65], v[68:69], v[64:65]
	v_pk_fma_f32 v[72:73], v[122:123], v[170:171], v[72:73]
	v_pk_mul_f32 v[64:65], v[64:65], s[36:37] op_sel_hi:[1,0]
	v_pk_mul_f32 v[68:69], v[70:71], v[78:79]
	v_lshlrev_b32_e32 v70, 16, v66
	v_and_b32_e32 v71, 0xffff0000, v66
	v_pk_fma_f32 v[70:71], v[142:143], v[70:71], v[72:73]
	v_cvt_pk_bf16_f32 v64, v64, v65
	v_mul_f32_e32 v65, 0xbfb8aa3b, v70
	v_exp_f32_e32 v66, v65
	v_mul_f32_e32 v65, 0xbfb8aa3b, v71
	v_exp_f32_e32 v72, v65
	v_pk_mul_f32 v[68:69], v[68:69], s[36:37] op_sel_hi:[1,0]
	v_add_f32_e32 v66, 1.0, v66
	v_cvt_pk_bf16_f32 v65, v68, v69
	v_add_f32_e32 v78, 1.0, v72
	v_pk_fma_f32 v[72:73], v[74:75], v[166:167], v[92:93]
	v_lshlrev_b32_e32 v68, 16, v67
	v_pk_fma_f32 v[72:73], v[100:101], v[168:169], v[72:73]
	v_and_b32_e32 v69, 0xffff0000, v67
	v_pk_fma_f32 v[72:73], v[124:125], v[172:173], v[72:73]
	v_rcp_f32_e32 v66, v66
	v_pk_fma_f32 v[68:69], v[144:145], v[68:69], v[72:73]
	s_nop 0
	v_mul_f32_e32 v67, 0xbfb8aa3b, v68
	v_exp_f32_e32 v72, v67
	v_mul_f32_e32 v67, 0xbfb8aa3b, v69
	v_exp_f32_e32 v73, v67
	v_rcp_f32_e32 v67, v78
	v_add_f32_e32 v72, 1.0, v72
	v_rcp_f32_e32 v72, v72
	v_add_f32_e32 v73, 1.0, v73
	v_rcp_f32_e32 v73, v73
	v_pk_mul_f32 v[66:67], v[70:71], v[66:67]
	v_pk_mul_f32 v[68:69], v[68:69], v[72:73]
	v_pk_mul_f32 v[66:67], v[66:67], s[36:37] op_sel_hi:[1,0]
	v_pk_mul_f32 v[68:69], v[68:69], s[36:37] op_sel_hi:[1,0]
	v_cvt_pk_bf16_f32 v66, v66, v67
	v_cvt_pk_bf16_f32 v67, v68, v69
	ds_write_b128 v77, v[64:67]
	v_lshl_add_u64 v[64:65], v[106:107], 0, s[46:47]
	v_add_u32_e32 v66, v76, v81
; #define LAS __attribute__((address_space(3)))
; DI void lbar() { asm volatile("s_waitcnt lgkmcnt(0)" ::: "memory"); __builtin_amdgcn_s_barrier(); asm volatile("" ::: "memory"); }
; template <bool P2>
; DI void ml_pass(LAS unsigned char* lds, const bf16_t* PROJ, const float* GATES, float* STATE, float* SC, bf16_t* YM,
;                 const float* convw, const float* convb, const float* ogain, int G, int bid) {
;     ...
;             for (int it = 0; it < 2; ++it) { const int idx = tid + 512 * it, sp2 = idx & 31, pc2 = idx >> 5;
;                 const bf16_t* vb = PROJ + (row0 + 2 * sp2) * 3072 + 1024 + 256 * h + 8 * pc2;
;                 const u32x4 r0 = *(const u32x4*)vb, r1 = *(const u32x4*)(vb + 3072);
;                 LAS unsigned* dst = Vt32 + (8 * pc2) * 36 + sp2;
;                 dst[0 * 36] = (r0.x & 0xffffu) | (r1.x << 16); dst[1 * 36] = (r0.x >> 16) | (r1.x & 0xffff0000u);
;                 dst[2 * 36] = (r0.y & 0xffffu) | (r1.y << 16); dst[3 * 36] = (r0.y >> 16) | (r1.y & 0xffff0000u);
;                 dst[4 * 36] = (r0.z & 0xffffu) | (r1.z << 16); dst[5 * 36] = (r0.z >> 16) | (r1.z & 0xffff0000u);
;                 dst[6 * 36] = (r0.w & 0xffffu) | (r1.w << 16); dst[7 * 36] = (r0.w >> 16) | (r1.w & 0xffff0000u); }
;             lbar();
;     ...
;                     const int t2 = (tid - 256) >> 2, qtr = tid & 3; float s = 0.f;
; #pragma unroll
;                     for (int q8 = 0; q8 < 4; ++q8) { const int d0 = 32 * qtr + 8 * q8; const u32x4 qv = *(const LAS u32x4*)(Qs + t2 * 136 + d0); const f32x4 n0 = *(const LAS f32x4*)(ns + d0), n1 = *(const LAS f32x4*)(ns + d0 + 4);
;                         s += bflo(qv.x) * n0[0] + bfhi(qv.x) * n0[1] + bflo(qv.y) * n0[2] + bfhi(qv.y) * n0[3] + bflo(qv.z) * n1[0] + bfhi(qv.z) * n1[1] + bflo(qv.w) * n1[2] + bfhi(qv.w) * n1[3]; }
;                     s += __shfl_xor(s, 1); s += __shfl_xor(s, 2);
;                     if (qtr == 0) dq[t2] = s;
.LBB0_149:
	v_cndmask_b32_e64 v67, 0, 1, s[48:49]
	v_cmp_ne_u32_e64 s[0:1], 1, v67
	v_mov_b32_e32 v67, s2
	v_lshrrev_b32_e32 v67, 2, v67
	v_add_u32_e32 v76, v67, v179
	v_ashrrev_i32_e32 v77, 31, v76
	v_lshl_add_u64 v[72:73], v[76:77], 1, v[64:65]
	global_load_dwordx4 v[68:71], v[72:73], off offset:2048
	v_add_co_u32_e32 v72, vcc, 0x2000, v72
	v_mad_u64_u32 v[76:77], s[48:49], v76, s25, v[66:67]
	s_nop 0
	v_addc_co_u32_e32 v73, vcc, 0, v73, vcc
	global_load_dwordx4 v[72:75], v[72:73], off
	s_movk_i32 s2, 0x200
	s_mov_b64 s[48:49], 0
	s_and_b64 vcc, exec, s[0:1]
	s_waitcnt vmcnt(1)
	v_and_b32_e32 v67, 0xffff, v68
	v_lshrrev_b32_e32 v68, 16, v68
	s_waitcnt vmcnt(0)
	v_lshl_or_b32 v67, v72, 16, v67
	v_and_or_b32 v68, v72, s27, v68
	v_add_u32_e32 v72, 0xd000, v76
	ds_write2_b32 v72, v67, v68 offset1:36
	v_and_b32_e32 v67, 0xffff, v69
	v_lshrrev_b32_e32 v68, 16, v69
	v_lshl_or_b32 v67, v73, 16, v67
	v_and_or_b32 v68, v73, s27, v68
	ds_write2_b32 v72, v67, v68 offset0:72 offset1:108
	v_and_b32_e32 v67, 0xffff, v70
	v_lshrrev_b32_e32 v68, 16, v70
	v_lshl_or_b32 v67, v74, 16, v67
	v_and_or_b32 v68, v74, s27, v68
	ds_write2_b32 v72, v67, v68 offset0:144 offset1:180
	v_and_b32_e32 v67, 0xffff, v71
	v_lshrrev_b32_e32 v68, 16, v71
	v_lshl_or_b32 v67, v75, 16, v67
	v_and_or_b32 v68, v75, s27, v68
	ds_write2_b32 v72, v67, v68 offset0:216 offset1:252
	s_cbranch_vccz .LBB0_149
	s_waitcnt lgkmcnt(0)
	s_barrier
	s_ashr_i32 s47, s77, 6
	s_cmp_gt_i32 s47, 3
	s_mov_b64 s[0:1], -1
	s_cbranch_scc0 .LBB0_154
	v_add_u32_e32 v64, 0xffffff00, v133
	v_ashrrev_i32_e32 v64, 2, v64
	v_and_b32_e32 v78, 3, v133
	v_mul_lo_u32 v65, v64, s24
	v_lshlrev_b32_e32 v66, 6, v78
	v_add3_u32 v65, 0, v65, v66
	ds_read_b128 v[66:69], v65
	ds_read_b128 v[70:73], v65 offset:16
	ds_read_b128 v[74:77], v65 offset:32
	ds_read_b128 v[82:85], v65 offset:48
	v_lshl_add_u32 v65, v78, 7, 0
	v_add_u32_e32 v65, 0x20800, v65
	ds_read_b128 v[86:89], v65
	ds_read_b128 v[90:93], v65 offset:16
	ds_read_b128 v[94:97], v65 offset:32
	ds_read_b128 v[98:101], v65 offset:48
	s_waitcnt lgkmcnt(7)
	v_lshlrev_b32_e32 v79, 16, v66
	v_and_b32_e32 v66, 0xffff0000, v66
	s_waitcnt lgkmcnt(3)
	v_mul_f32_e32 v66, v87, v66
	v_fmac_f32_e32 v66, v86, v79
	v_lshlrev_b32_e32 v79, 16, v67
	v_fmac_f32_e32 v66, v88, v79
	v_and_b32_e32 v67, 0xffff0000, v67
	v_fmac_f32_e32 v66, v89, v67
	v_lshlrev_b32_e32 v67, 16, v68
	s_waitcnt lgkmcnt(2)
	v_fmac_f32_e32 v66, v90, v67
	v_and_b32_e32 v67, 0xffff0000, v68
	v_fmac_f32_e32 v66, v91, v67
	v_lshlrev_b32_e32 v67, 16, v69
	v_fmac_f32_e32 v66, v92, v67
	v_and_b32_e32 v67, 0xffff0000, v69
	v_fmac_f32_e32 v66, v93, v67
	v_and_b32_e32 v67, 0xffff0000, v70
	v_add_f32_e32 v79, 0, v66
	v_lshlrev_b32_e32 v66, 16, v70
	s_waitcnt lgkmcnt(1)
	v_mul_f32_e32 v70, v95, v67
	v_fmac_f32_e32 v70, v94, v66
	v_lshlrev_b32_e32 v66, 16, v71
	v_fmac_f32_e32 v70, v96, v66
	v_and_b32_e32 v66, 0xffff0000, v71
	v_fmac_f32_e32 v70, v97, v66
	v_lshlrev_b32_e32 v66, 16, v72
	s_waitcnt lgkmcnt(0)
	v_fmac_f32_e32 v70, v98, v66
	v_and_b32_e32 v66, 0xffff0000, v72
	v_fmac_f32_e32 v70, v99, v66
	v_lshlrev_b32_e32 v66, 16, v73
	v_fmac_f32_e32 v70, v100, v66
	v_and_b32_e32 v66, 0xffff0000, v73
	v_fmac_f32_e32 v70, v101, v66
	ds_read_b128 v[66:69], v65 offset:64
	v_add_f32_e32 v79, v79, v70
	ds_read_b128 v[70:73], v65 offset:80
	v_lshlrev_b32_e32 v81, 16, v74
	v_and_b32_e32 v74, 0xffff0000, v74
	s_waitcnt lgkmcnt(1)
	v_mul_f32_e32 v74, v67, v74
	v_fmac_f32_e32 v74, v66, v81
	v_lshlrev_b32_e32 v66, 16, v75
	v_fmac_f32_e32 v74, v68, v66
	v_and_b32_e32 v66, 0xffff0000, v75
	v_fmac_f32_e32 v74, v69, v66
	v_lshlrev_b32_e32 v66, 16, v76
	s_waitcnt lgkmcnt(0)
	v_fmac_f32_e32 v74, v70, v66
	v_and_b32_e32 v66, 0xffff0000, v76
	v_fmac_f32_e32 v74, v71, v66
	v_lshlrev_b32_e32 v66, 16, v77
	v_fmac_f32_e32 v74, v72, v66
	v_and_b32_e32 v66, 0xffff0000, v77
	v_fmac_f32_e32 v74, v73, v66
	ds_read_b128 v[66:69], v65 offset:96
	ds_read_b128 v[70:73], v65 offset:112
	v_and_b32_e32 v75, 0xffff0000, v82
	v_lshlrev_b32_e32 v65, 16, v82
	v_add_f32_e32 v74, v79, v74
	s_waitcnt lgkmcnt(1)
	v_mul_f32_e32 v67, v67, v75
	v_fmac_f32_e32 v67, v66, v65
	v_lshlrev_b32_e32 v65, 16, v83
	v_fmac_f32_e32 v67, v68, v65
	v_and_b32_e32 v65, 0xffff0000, v83
	v_fmac_f32_e32 v67, v69, v65
	v_lshlrev_b32_e32 v65, 16, v84
	s_waitcnt lgkmcnt(0)
	v_fmac_f32_e32 v67, v70, v65
	v_and_b32_e32 v65, 0xffff0000, v84
	v_fmac_f32_e32 v67, v71, v65
	v_lshlrev_b32_e32 v65, 16, v85
	v_fmac_f32_e32 v67, v72, v65
	v_and_b32_e32 v65, 0xffff0000, v85
	v_fmac_f32_e32 v67, v73, v65
	v_add_f32_e32 v65, v74, v67
	v_xor_b32_e32 v66, 1, v232
	v_add_u32_e32 v67, 64, v126
	v_cmp_lt_i32_e32 vcc, v66, v67
	s_nop 1
	v_cndmask_b32_e32 v66, v232, v66, vcc
	v_lshlrev_b32_e32 v66, 2, v66
	ds_bpermute_b32 v66, v66, v65
	s_waitcnt lgkmcnt(0)
	v_add_f32_e32 v65, v65, v66
	v_xor_b32_e32 v66, 2, v232
	v_cmp_lt_i32_e32 vcc, v66, v67
	s_nop 1
	v_cndmask_b32_e32 v66, v232, v66, vcc
	v_lshlrev_b32_e32 v66, 2, v66
	ds_bpermute_b32 v66, v66, v65
	v_cmp_eq_u32_e32 vcc, 0, v78
	s_and_saveexec_b64 s[0:1], vcc
	s_cbranch_execz .LBB0_153
	v_lshl_add_u32 v64, v64, 2, 0
	s_waitcnt lgkmcnt(0)
	v_add_f32_e32 v65, v65, v66
	v_add_u32_e32 v64, 0x20b00, v64
	ds_write_b32 v64, v65

; template <bool P2>
; DI void ml_pass(LAS unsigned char* lds, const bf16_t* PROJ, const float* GATES, float* STATE, float* SC, bf16_t* YM,
;                 const float* convw, const float* convb, const float* ogain, int G, int bid) {
;     ...
;             const int sp = tid & 31, pc = tid >> 5;
;             {
;                 u32x4 xr[5];
;                 const bf16_t* kb = PROJ + (row0 + 2 * sp) * 3072 + 512 + 128 * h + 8 * pc;
; #pragma unroll
;                 for (int r = 0; r < 5; ++r) { const int tt = t0 + 2 * sp - 3 + r; xr[r] = (tt >= 0) ? *(const u32x4*)(kb + ((long)r - 3) * 3072) : (u32x4){0u, 0u, 0u, 0u}; }
.LBB0_198:
	v_and_b32_e32 v147, 31, v146
	v_lshrrev_b32_e32 v160, 3, v146
	v_and_b32_e32 v160, 31, v160
	v_lshlrev_b32_e32 v112, 1, v160
	v_or_b32_e32 v66, s2, v112
	v_mov_b64_e32 v[64:65], s[28:29]
	v_mad_u64_u32 v[136:137], s[58:59], v66, s79, v[64:65]
	v_lshrrev_b32_e32 v161, 5, v146
	v_and_b32_e32 v149, 7, v146
	v_and_or_b32 v149, v161, 8, v149
	v_lshlrev_b32_e32 v149, 3, v149
	v_mad_i32_i24 v137, s1, v231, v137
	v_and_b32_e32 v140, -8, v149
	v_lshl_add_u64 v[64:65], v[136:137], 0, s[34:35]
	v_ashrrev_i32_e32 v141, 31, v140
	v_or_b32_e32 v69, s0, v112
	v_lshl_add_u64 v[80:81], v[140:141], 1, v[64:65]
	v_cmp_lt_u32_e32 vcc, 2, v69
	v_mov_b32_e32 v68, 0
	v_mov_b32_e32 v64, 0
	v_mov_b32_e32 v65, 0
	v_mov_b32_e32 v66, 0
	v_mov_b32_e32 v67, 0
	s_and_saveexec_b64 s[0:1], vcc
	s_cbranch_execz .LBB0_200
	v_add_co_u32_e32 v64, vcc, 0xffffc000, v80
	s_nop 1
	v_addc_co_u32_e32 v65, vcc, -1, v81, vcc
	global_load_dwordx4 v[64:67], v[64:65], off offset:-1024

; #define LAS __attribute__((address_space(3)))
; DI unsigned pk2(float lo, float hi) { f32x2n v = {lo, hi}; bf16x2n b = __builtin_convertvector(v, bf16x2n); return __builtin_bit_cast(unsigned, b); }
; template <bool P2>
; DI void ml_pass(LAS unsigned char* lds, const bf16_t* PROJ, const float* GATES, float* STATE, float* SC, bf16_t* YM,
;                 const float* convw, const float* convb, const float* ogain, int G, int bid) {
;     ...
;             const float bcum = wave_scan_sum(lf);
;             const float gq = li - bcum; const float pm = wave_scan_max(gq);
;             const float b_last = __builtin_bit_cast(float, __builtin_amdgcn_readlane(__builtin_bit_cast(int, bcum), 63)), pm63 = __builtin_bit_cast(float, __builtin_amdgcn_readlane(__builtin_bit_cast(int, pm), 63));
;             const float m_new = fmaxf(b_last + m_prev, b_last + pm63);
;             const float decay = __expf(b_last + m_prev - m_new);
;             const float wk = __expf(b_last + gq - m_new);
;             const float mt = fmaxf(bcum + m_prev, bcum + pm);
;             const float inter = __expf(bcum + m_prev - mt);
;             if (w == 0) gs[lane] = gq;
;             const int sp = tid & 31, pc = tid >> 5;
;             {
;                 u32x4 xr[5];
;                 const bf16_t* kb = PROJ + (row0 + 2 * sp) * 3072 + 512 + 128 * h + 8 * pc;
; #pragma unroll
;                 for (int r = 0; r < 5; ++r) { const int tt = t0 + 2 * sp - 3 + r; xr[r] = (tt >= 0) ? *(const u32x4*)(kb + ((long)r - 3) * 3072) : (u32x4){0u, 0u, 0u, 0u}; }
;                 float y0[8], y1[8]; conv2(xr, cw + 640, 8 * pc, y0, y1);
;                 if (P2) { u32x4 o; o.x = pk2(y0[0], y0[1]); o.y = pk2(y0[2], y0[3]); o.z = pk2(y0[4], y0[5]); o.w = pk2(y0[6], y0[7]); *(LAS u32x4*)(Ks + (2 * sp) * 136 + 8 * pc) = o;
;                     o.x = pk2(y1[0], y1[1]); o.y = pk2(y1[2], y1[3]); o.z = pk2(y1[4], y1[5]); o.w = pk2(y1[6], y1[7]); *(LAS u32x4*)(Ks + (2 * sp + 1) * 136 + 8 * pc) = o; }
;                 const float wk0 = __shfl(wk, 2 * sp), wk1 = __shfl(wk, 2 * sp + 1);
; #pragma unroll
;                 for (int j = 0; j < 8; ++j) Kt32[(8 * pc + j) * 36 + sp] = pk2(y0[j] * wk0, y1[j] * wk1);
.LBB0_204:
	s_or_b64 exec, exec, s[58:59]
	v_mov_b32_e32 v77, s57
	v_add_f32_e32 v148, s71, v134
	v_add_f32_e32 v77, s71, v77
	v_max_f32_e32 v134, v148, v77
	v_add_f32_e32 v76, s71, v76
	v_sub_f32_e32 v76, v76, v134
	v_mul_f32_e32 v76, 0x3fb8aa3b, v76
	v_exp_f32_e32 v139, v76
	global_load_dwordx4 v[76:79], v[80:81], off offset:1024
	v_add_co_u32_e32 v80, vcc, s37, v80
	s_waitcnt lgkmcnt(0)
	v_lshl_add_u32 v84, v140, 2, 0
	v_addc_co_u32_e32 v81, vcc, 0, v81, vcc
	global_load_dwordx4 v[80:83], v[80:81], off offset:3072
	v_add_u32_e32 v88, 0x22000, v84
	s_waitcnt vmcnt(2)
	v_lshlrev_b32_e32 v151, 16, v68
	v_lshlrev_b32_e32 v150, 16, v64
	ds_read_b128 v[108:111], v88 offset:2048
	ds_read_b128 v[122:125], v88
	ds_read_b128 v[84:87], v88 offset:16
	ds_read_b128 v[118:121], v88 offset:512
	ds_read_b128 v[114:117], v88 offset:1024
	ds_read_b128 v[104:107], v88 offset:1536
	ds_read_b128 v[100:103], v88 offset:2064
	ds_read_b128 v[96:99], v88 offset:528
	ds_read_b128 v[92:95], v88 offset:1040
	ds_read_b128 v[88:91], v88 offset:1552
	v_lshlrev_b32_e32 v153, 16, v72
	v_mov_b32_e32 v152, v151
	s_waitcnt lgkmcnt(0)
	v_pk_fma_f32 v[150:151], v[122:123], v[150:151], v[108:109] op_sel_hi:[0,1,0]
	v_mov_b32_e32 v154, v153
	v_pk_fma_f32 v[150:151], v[118:119], v[152:153], v[150:151] op_sel_hi:[0,1,1]
	v_and_or_b32 v112, v232, 64, v112
	v_lshlrev_b32_e32 v112, 2, v112
	ds_bpermute_b32 v138, v112, v139
	v_or_b32_e32 v112, 4, v112
	ds_bpermute_b32 v139, v112, v139
	v_lshl_add_u32 v112, v160, 2, 0
	s_mov_b32 s57, s35
	s_mov_b32 s73, 0
	s_mov_b64 s[58:59], -1
	s_waitcnt vmcnt(1)
	v_lshlrev_b32_e32 v155, 16, v76
	v_mov_b32_e32 v156, v155
	v_pk_fma_f32 v[150:151], v[114:115], v[154:155], v[150:151] op_sel_hi:[0,1,1]
	v_and_b32_e32 v155, 0xffff0000, v76
	s_waitcnt vmcnt(0)
	v_lshlrev_b32_e32 v157, 16, v80
	v_pk_fma_f32 v[150:151], v[104:105], v[156:157], v[150:151] op_sel_hi:[0,1,1]
	v_mul_f32_e32 v141, 0xbfb8aa3b, v150
	v_exp_f32_e32 v141, v141
	v_and_b32_e32 v157, 0xffff0000, v80
	v_mov_b32_e32 v156, v155
	v_add_f32_e32 v141, 1.0, v141
	v_rcp_f32_e32 v152, v141
	v_mul_f32_e32 v141, 0xbfb8aa3b, v151
	v_exp_f32_e32 v141, v141
	s_nop 0
	v_add_f32_e32 v141, 1.0, v141
	v_rcp_f32_e32 v153, v141
	v_mad_u64_u32 v[140:141], s[0:1], v140, s25, v[112:113]
	v_pk_mul_f32 v[150:151], v[150:151], v[152:153]
	s_waitcnt lgkmcnt(0)
	v_pk_mul_f32 v[150:151], v[150:151], v[138:139]
	v_and_b32_e32 v153, 0xffff0000, v72
	v_cvt_pk_bf16_f32 v158, v150, v151
	v_and_b32_e32 v151, 0xffff0000, v68
	v_and_b32_e32 v150, 0xffff0000, v64
	v_mov_b32_e32 v152, v151
	v_pk_fma_f32 v[108:109], v[122:123], v[150:151], v[108:109] op_sel:[1,0,1]
	v_mov_b32_e32 v154, v153
	v_pk_fma_f32 v[108:109], v[118:119], v[152:153], v[108:109] op_sel:[1,0,0]
	v_lshlrev_b32_e32 v119, 16, v81
	v_pk_fma_f32 v[108:109], v[114:115], v[154:155], v[108:109] op_sel:[1,0,0]
	v_lshlrev_b32_e32 v115, 16, v77
	v_pk_fma_f32 v[104:105], v[104:105], v[156:157], v[108:109] op_sel:[1,0,0]
	v_mov_b32_e32 v118, v115
	v_mul_f32_e32 v64, 0xbfb8aa3b, v104
	v_exp_f32_e32 v64, v64
	v_and_b32_e32 v77, 0xffff0000, v77
	v_and_b32_e32 v81, 0xffff0000, v81
	v_mov_b32_e32 v80, v77
	v_add_f32_e32 v64, 1.0, v64
	v_rcp_f32_e32 v108, v64
	v_mul_f32_e32 v64, 0xbfb8aa3b, v105
	v_exp_f32_e32 v64, v64
	s_nop 0
	v_add_f32_e32 v64, 1.0, v64
	v_rcp_f32_e32 v109, v64
	v_add_u32_e32 v64, 0x8800, v140
	v_pk_mul_f32 v[104:105], v[104:105], v[108:109]
	s_nop 0
	v_pk_mul_f32 v[104:105], v[104:105], v[138:139]
	v_lshlrev_b32_e32 v109, 16, v73
	v_cvt_pk_bf16_f32 v68, v104, v105
	v_lshlrev_b32_e32 v104, 16, v65
	v_lshlrev_b32_e32 v105, 16, v69
	v_mov_b32_e32 v108, v105
	v_pk_fma_f32 v[104:105], v[124:125], v[104:105], v[110:111] op_sel_hi:[0,1,0]
	v_mov_b32_e32 v114, v109
	v_pk_fma_f32 v[104:105], v[120:121], v[108:109], v[104:105] op_sel_hi:[0,1,1]
	v_pk_fma_f32 v[104:105], v[116:117], v[114:115], v[104:105] op_sel_hi:[0,1,1]
	v_pk_fma_f32 v[104:105], v[106:107], v[118:119], v[104:105] op_sel_hi:[0,1,1]
	ds_write2_b32 v64, v158, v68 offset1:36
	v_mul_f32_e32 v68, 0xbfb8aa3b, v104
	v_exp_f32_e32 v68, v68
	v_and_b32_e32 v69, 0xffff0000, v69
	v_mov_b32_e32 v106, v111
	v_and_b32_e32 v73, 0xffff0000, v73
	v_add_f32_e32 v68, 1.0, v68
	v_rcp_f32_e32 v108, v68
	v_mul_f32_e32 v68, 0xbfb8aa3b, v105
	v_exp_f32_e32 v68, v68
	v_mov_b32_e32 v72, v69
	v_mov_b32_e32 v76, v73
	v_add_f32_e32 v68, 1.0, v68
	v_rcp_f32_e32 v109, v68
	v_and_b32_e32 v68, 0xffff0000, v65
	v_pk_mul_f32 v[104:105], v[104:105], v[108:109]
	s_nop 0
	v_pk_mul_f32 v[104:105], v[104:105], v[138:139]
	s_nop 0
	v_cvt_pk_bf16_f32 v105, v104, v105
	v_mov_b32_e32 v104, v125
	v_pk_fma_f32 v[68:69], v[104:105], v[68:69], v[106:107] op_sel_hi:[0,1,0]
	v_mov_b32_e32 v104, v121
	v_pk_fma_f32 v[68:69], v[104:105], v[72:73], v[68:69] op_sel_hi:[0,1,1]
	v_mov_b32_e32 v72, v117
	v_pk_fma_f32 v[68:69], v[72:73], v[76:77], v[68:69] op_sel_hi:[0,1,1]
	v_mov_b32_e32 v72, v107
	v_pk_fma_f32 v[68:69], v[72:73], v[80:81], v[68:69] op_sel_hi:[0,1,1]
	v_mul_f32_e32 v65, 0xbfb8aa3b, v68
	v_exp_f32_e32 v65, v65
	v_lshlrev_b32_e32 v77, 16, v78
	v_lshlrev_b32_e32 v81, 16, v82
	v_mov_b32_e32 v80, v77
	v_add_f32_e32 v65, 1.0, v65
	v_rcp_f32_e32 v72, v65
	v_mul_f32_e32 v65, 0xbfb8aa3b, v69
	v_exp_f32_e32 v65, v65
	s_nop 0
	v_add_f32_e32 v65, 1.0, v65
	v_rcp_f32_e32 v73, v65
	s_nop 0
	v_pk_mul_f32 v[68:69], v[68:69], v[72:73]
	s_nop 0
	v_pk_mul_f32 v[68:69], v[68:69], v[138:139]
	v_lshlrev_b32_e32 v73, 16, v74
	v_cvt_pk_bf16_f32 v65, v68, v69
	v_lshlrev_b32_e32 v69, 16, v70
	v_lshlrev_b32_e32 v68, 16, v66
	v_mov_b32_e32 v72, v69
	v_pk_fma_f32 v[68:69], v[84:85], v[68:69], v[100:101] op_sel_hi:[0,1,0]
	v_mov_b32_e32 v76, v73
; template <bool P2>
; DI void ml_pass(LAS unsigned char* lds, const bf16_t* PROJ, const float* GATES, float* STATE, float* SC, bf16_t* YM,
;                 const float* convw, const float* convb, const float* ogain, int G, int bid) {
;     ...
;                 float y0[8], y1[8]; conv2(xr, cw + 640, 8 * pc, y0, y1);
;                 if (P2) { u32x4 o; o.x = pk2(y0[0], y0[1]); o.y = pk2(y0[2], y0[3]); o.z = pk2(y0[4], y0[5]); o.w = pk2(y0[6], y0[7]); *(LAS u32x4*)(Ks + (2 * sp) * 136 + 8 * pc) = o;
;                     o.x = pk2(y1[0], y1[1]); o.y = pk2(y1[2], y1[3]); o.z = pk2(y1[4], y1[5]); o.w = pk2(y1[6], y1[7]); *(LAS u32x4*)(Ks + (2 * sp + 1) * 136 + 8 * pc) = o; }
;                 const float wk0 = __shfl(wk, 2 * sp), wk1 = __shfl(wk, 2 * sp + 1);
; #pragma unroll
;                 for (int j = 0; j < 8; ++j) Kt32[(8 * pc + j) * 36 + sp] = pk2(y0[j] * wk0, y1[j] * wk1);
;                 asm volatile("" ::: "memory");
;                 if (P2) {
;                     const bf16_t* qb = PROJ + (row0 + 2 * sp) * 3072 + 128 * h + 8 * pc;
; #pragma unroll
;                     for (int r = 0; r < 5; ++r) { const int tt = t0 + 2 * sp - 3 + r; xr[r] = (tt >= 0) ? *(const u32x4*)(qb + ((long)r - 3) * 3072) : (u32x4){0u, 0u, 0u, 0u}; }
;                     conv2(xr, cw, 8 * pc, y0, y1);
;                     const float qs = 0.08838834764831845f;
;                     u32x4 o; o.x = pk2(y0[0] * qs, y0[1] * qs); o.y = pk2(y0[2] * qs, y0[3] * qs); o.z = pk2(y0[4] * qs, y0[5] * qs); o.w = pk2(y0[6] * qs, y0[7] * qs); *(LAS u32x4*)(Qs + (2 * sp) * 136 + 8 * pc) = o;
;                     o.x = pk2(y1[0] * qs, y1[1] * qs); o.y = pk2(y1[2] * qs, y1[3] * qs); o.z = pk2(y1[4] * qs, y1[5] * qs); o.w = pk2(y1[6] * qs, y1[7] * qs); *(LAS u32x4*)(Qs + (2 * sp + 1) * 136 + 8 * pc) = o;
;                 }
;             }
;             asm volatile("" ::: "memory");
; #pragma unroll 1
;             for (int it = 0; it < 2; ++it) { const int idx = tid + 512 * it, sp2 = idx & 31, pc2 = idx >> 5;
;                 const bf16_t* vb = PROJ + (row0 + 2 * sp2) * 3072 + 1024 + 256 * h + 8 * pc2;
;                 const u32x4 r0 = *(const u32x4*)vb, r1 = *(const u32x4*)(vb + 3072);
;                 LAS unsigned* dst = Vt32 + (8 * pc2) * 36 + sp2;
;                 dst[0 * 36] = (r0.x & 0xffffu) | (r1.x << 16); dst[1 * 36] = (r0.x >> 16) | (r1.x & 0xffff0000u);
	v_pk_fma_f32 v[68:69], v[96:97], v[72:73], v[68:69] op_sel_hi:[0,1,1]
	v_pk_fma_f32 v[68:69], v[92:93], v[76:77], v[68:69] op_sel_hi:[0,1,1]
	v_pk_fma_f32 v[68:69], v[88:89], v[80:81], v[68:69] op_sel_hi:[0,1,1]
	ds_write2_b32 v64, v105, v65 offset0:72 offset1:108
	v_mul_f32_e32 v65, 0xbfb8aa3b, v68
	v_exp_f32_e32 v65, v65
	v_and_b32_e32 v77, 0xffff0000, v78
	v_and_b32_e32 v81, 0xffff0000, v82
	v_mov_b32_e32 v80, v77
	v_add_f32_e32 v65, 1.0, v65
	v_rcp_f32_e32 v72, v65
	v_mul_f32_e32 v65, 0xbfb8aa3b, v69
	v_exp_f32_e32 v65, v65
	s_nop 0
	v_add_f32_e32 v65, 1.0, v65
	v_rcp_f32_e32 v73, v65
	s_nop 0
	v_pk_mul_f32 v[68:69], v[68:69], v[72:73]
	s_nop 0
	v_pk_mul_f32 v[68:69], v[68:69], v[138:139]
	v_and_b32_e32 v73, 0xffff0000, v74
	v_cvt_pk_bf16_f32 v65, v68, v69
	v_and_b32_e32 v69, 0xffff0000, v70
	v_and_b32_e32 v68, 0xffff0000, v66
	v_mov_b32_e32 v72, v69
	v_pk_fma_f32 v[68:69], v[84:85], v[68:69], v[100:101] op_sel:[1,0,1]
	v_mov_b32_e32 v76, v73
	v_pk_fma_f32 v[68:69], v[96:97], v[72:73], v[68:69] op_sel:[1,0,0]
	v_mov_b32_e32 v74, v103
	v_pk_fma_f32 v[68:69], v[92:93], v[76:77], v[68:69] op_sel:[1,0,0]
	v_lshlrev_b32_e32 v77, 16, v83
	v_pk_fma_f32 v[68:69], v[88:89], v[80:81], v[68:69] op_sel:[1,0,0]
	s_nop 0
	v_mul_f32_e32 v66, 0xbfb8aa3b, v68
	v_exp_f32_e32 v66, v66
	s_nop 0
	v_add_f32_e32 v66, 1.0, v66
	v_rcp_f32_e32 v72, v66
	v_mul_f32_e32 v66, 0xbfb8aa3b, v69
	v_exp_f32_e32 v66, v66
	s_nop 0
	v_add_f32_e32 v66, 1.0, v66
	v_rcp_f32_e32 v73, v66
	s_nop 0
	v_pk_mul_f32 v[68:69], v[68:69], v[72:73]
	s_nop 0
	v_pk_mul_f32 v[68:69], v[68:69], v[138:139]
	v_lshlrev_b32_e32 v73, 16, v79
	v_cvt_pk_bf16_f32 v66, v68, v69
	ds_write2_b32 v64, v65, v66 offset0:144 offset1:180
	v_lshlrev_b32_e32 v64, 16, v67
	v_lshlrev_b32_e32 v65, 16, v71
	v_lshlrev_b32_e32 v69, 16, v75
	v_mov_b32_e32 v68, v65
	v_pk_fma_f32 v[64:65], v[86:87], v[64:65], v[102:103] op_sel_hi:[0,1,0]
	v_mov_b32_e32 v72, v69
	v_pk_fma_f32 v[64:65], v[98:99], v[68:69], v[64:65] op_sel_hi:[0,1,1]
	v_mov_b32_e32 v76, v73
	v_pk_fma_f32 v[64:65], v[94:95], v[72:73], v[64:65] op_sel_hi:[0,1,1]
	v_pk_fma_f32 v[64:65], v[90:91], v[76:77], v[64:65] op_sel_hi:[0,1,1]
	v_mul_f32_e32 v66, 0xbfb8aa3b, v64
	v_exp_f32_e32 v66, v66
	v_mov_b32_e32 v72, v87
	v_add_f32_e32 v66, 1.0, v66
	v_rcp_f32_e32 v68, v66
	v_mul_f32_e32 v66, 0xbfb8aa3b, v65
	v_exp_f32_e32 v66, v66
	s_nop 0
	v_add_f32_e32 v66, 1.0, v66
	v_rcp_f32_e32 v69, v66
	s_nop 0
	v_pk_mul_f32 v[64:65], v[64:65], v[68:69]
	s_nop 0
	v_pk_mul_f32 v[64:65], v[64:65], v[138:139]
	v_and_b32_e32 v69, 0xffff0000, v79
	v_cvt_pk_bf16_f32 v64, v64, v65
	ds_write_b32 v140, v64 offset:35680
	v_and_b32_e32 v65, 0xffff0000, v71
	v_and_b32_e32 v64, 0xffff0000, v67
	v_and_b32_e32 v67, 0xffff0000, v75
	v_mov_b32_e32 v66, v65
	v_pk_fma_f32 v[64:65], v[72:73], v[64:65], v[74:75] op_sel_hi:[0,1,0]
	v_mov_b32_e32 v72, v99
	v_mov_b32_e32 v68, v67
	v_pk_fma_f32 v[64:65], v[72:73], v[66:67], v[64:65] op_sel_hi:[0,1,1]
	v_mov_b32_e32 v66, v95
	v_and_b32_e32 v71, 0xffff0000, v83
	v_mov_b32_e32 v70, v69
	v_pk_fma_f32 v[64:65], v[66:67], v[68:69], v[64:65] op_sel_hi:[0,1,1]
	v_mov_b32_e32 v66, v91
	v_pk_fma_f32 v[64:65], v[66:67], v[70:71], v[64:65] op_sel_hi:[0,1,1]
	v_mul_f32_e32 v66, 0xbfb8aa3b, v64
	v_mul_f32_e32 v67, 0xbfb8aa3b, v65
	v_exp_f32_e32 v66, v66
	v_exp_f32_e32 v67, v67
	v_add_f32_e32 v66, 1.0, v66
	v_add_f32_e32 v67, 1.0, v67
	v_rcp_f32_e32 v66, v66
	v_rcp_f32_e32 v67, v67
	s_nop 0
	v_pk_mul_f32 v[64:65], v[64:65], v[66:67]
	s_nop 0
	v_pk_mul_f32 v[64:65], v[64:65], v[138:139]
	s_nop 0
	v_cvt_pk_bf16_f32 v66, v64, v65
	v_or_b32_e32 v64, 7, v149
	v_mad_u64_u32 v[64:65], s[0:1], v64, s25, v[112:113]
	ds_write_b32 v64, v66 offset:34816
	v_lshl_add_u64 v[64:65], v[136:137], 0, s[56:57]
.LBB0_205:
	v_cndmask_b32_e64 v66, 0, 1, s[58:59]
	v_cmp_ne_u32_e64 s[0:1], 1, v66
	v_mov_b32_e32 v66, s73
	v_lshrrev_b32_e32 v66, 2, v66
	v_add_u32_e32 v74, v66, v149
	v_ashrrev_i32_e32 v75, 31, v74
	v_lshl_add_u64 v[70:71], v[74:75], 1, v[64:65]
	global_load_dwordx4 v[66:69], v[70:71], off offset:2048
	v_add_co_u32_e32 v70, vcc, 0x2000, v70
	v_mad_u64_u32 v[74:75], s[58:59], v74, s25, v[112:113]
	s_nop 0
	v_addc_co_u32_e32 v71, vcc, 0, v71, vcc
	global_load_dwordx4 v[70:73], v[70:71], off
	s_movk_i32 s73, 0x200
	s_mov_b64 s[58:59], 0
	s_and_b64 vcc, exec, s[0:1]
	s_waitcnt vmcnt(1)
	v_and_b32_e32 v75, 0xffff, v66
	v_lshrrev_b32_e32 v66, 16, v66
	s_waitcnt vmcnt(0)
	v_lshl_or_b32 v75, v70, 16, v75
	v_and_or_b32 v66, v70, s27, v66
	v_add_u32_e32 v70, 0xd000, v74
	ds_write2_b32 v70, v75, v66 offset1:36
	v_and_b32_e32 v66, 0xffff, v67
	v_lshrrev_b32_e32 v67, 16, v67
	v_lshl_or_b32 v66, v71, 16, v66
	v_and_or_b32 v67, v71, s27, v67
	ds_write2_b32 v70, v66, v67 offset0:72 offset1:108
	v_and_b32_e32 v66, 0xffff, v68
	v_lshrrev_b32_e32 v67, 16, v68
	v_lshl_or_b32 v66, v72, 16, v66
	v_and_or_b32 v67, v72, s27, v67
	ds_write2_b32 v70, v66, v67 offset0:144 offset1:180
	v_and_b32_e32 v66, 0xffff, v69
	v_lshrrev_b32_e32 v67, 16, v69
	v_lshl_or_b32 v66, v73, 16, v66
	v_and_or_b32 v67, v73, s27, v67
	ds_write2_b32 v70, v66, v67 offset0:216 offset1:252
	s_cbranch_vccz .LBB0_205
	v_sub_f32_e32 v64, v148, v134
	v_mul_f32_e32 v64, 0x3fb8aa3b, v64
	v_exp_f32_e32 v80, v64
	s_lshr_b32 s0, s72, 1
	v_lshrrev_b32_e32 v65, 1, v146
	s_and_b32 s0, s0, 0xfffffe0
	v_and_b32_e32 v65, 16, v65
	s_waitcnt lgkmcnt(0)
	s_barrier
; #define LAS __attribute__((address_space(3)))
; DI f32x16 mfma32(bf16x8 a, bf16x8 b, f32x16 c) { return __builtin_amdgcn_mfma_f32_32x32x16_bf16(a, b, c, 0, 0, 0); }
; template <bool P2>
; DI void ml_pass(LAS unsigned char* lds, const bf16_t* PROJ, const float* GATES, float* STATE, float* SC, bf16_t* YM,
;                 const float* convw, const float* convb, const float* ogain, int G, int bid) {
;     ...
;             bf16x8 vf[4];
; #pragma unroll
;             for (int kq = 0; kq < 4; ++kq) vf[kq] = *(const LAS bf16x8*)(Vt + (32 * w + l31) * 72 + 16 * kq + 8 * hi);
;             if (P2) {
; #pragma unroll
;                 for (int kq = 0; kq < 4; ++kq)
; #pragma unroll
;                     for (int tt = 0; tt < 2; ++tt) { const bf16x8 wf = *(const LAS bf16x8*)(Ws + (32 * tt + l31) * 72 + 16 * kq + 8 * hi); oacc[tt] = mfma32(vf[kq], wf, oacc[tt]); }
;             }
;             asm volatile("" ::: "memory");
;             if (!P2 || c < 7) {
; #pragma unroll
;             for (int dt = 0; dt < 4; ++dt) {
; #pragma unroll
;                 for (int i = 0; i < 16; ++i) Ct[dt][i] *= decay;
; #pragma unroll
;                 for (int kq = 0; kq < 4; ++kq) { const bf16x8 kf = *(const LAS bf16x8*)(Kt + (32 * dt + l31) * 72 + 16 * kq + 8 * hi); Ct[dt] = mfma32(kf, vf[kq], Ct[dt]); }
;             }
;             }
	v_or_b32_e32 v64, s0, v147
	v_add_u32_e32 v82, 0, v65
	v_mad_u64_u32 v[64:65], s[0:1], v64, s25, v[82:83]
	ds_read_b128 v[76:79], v64 offset:53248
	ds_read_b128 v[72:75], v64 offset:53280
	ds_read_b128 v[68:71], v64 offset:53312
	ds_read_b128 v[64:67], v64 offset:53344
	v_pk_mul_f32 v[62:63], v[62:63], v[80:81] op_sel_hi:[1,0]
	v_mad_u32_u24 v81, v147, s25, v82
	ds_read_b128 v[82:85], v81 offset:34816
	ds_read_b128 v[86:89], v81 offset:34848
	v_pk_mul_f32 v[60:61], v[60:61], v[80:81] op_sel_hi:[1,0]
	v_pk_mul_f32 v[58:59], v[58:59], v[80:81] op_sel_hi:[1,0]
	v_pk_mul_f32 v[56:57], v[56:57], v[80:81] op_sel_hi:[1,0]
	v_pk_mul_f32 v[54:55], v[54:55], v[80:81] op_sel_hi:[1,0]
	v_pk_mul_f32 v[52:53], v[52:53], v[80:81] op_sel_hi:[1,0]
	v_pk_mul_f32 v[50:51], v[50:51], v[80:81] op_sel_hi:[1,0]
	v_pk_mul_f32 v[48:49], v[48:49], v[80:81] op_sel_hi:[1,0]
	v_pk_mul_f32 v[30:31], v[30:31], v[80:81] op_sel_hi:[1,0]
	v_pk_mul_f32 v[28:29], v[28:29], v[80:81] op_sel_hi:[1,0]
	s_waitcnt lgkmcnt(1)
	v_mfma_f32_32x32x16_bf16 v[48:63], v[82:85], v[76:79], v[48:63]
	v_mul_f32_e64 v26, v26, v80
	v_mul_f32_e64 v27, v27, v80
	v_mul_f32_e64 v24, v24, v80
	v_mul_f32_e64 v25, v25, v80
	v_mul_f32_e64 v22, v22, v80
	v_mul_f32_e64 v23, v23, v80
	v_pk_mul_f32 v[20:21], v[20:21], v[80:81] op_sel_hi:[1,0]
	v_pk_mul_f32 v[18:19], v[18:19], v[80:81] op_sel_hi:[1,0]
	v_pk_mul_f32 v[16:17], v[16:17], v[80:81] op_sel_hi:[1,0]
	v_pk_mul_f32 v[46:47], v[46:47], v[80:81] op_sel_hi:[1,0]
	s_waitcnt lgkmcnt(0)
	v_mfma_f32_32x32x16_bf16 v[48:63], v[86:89], v[72:75], v[48:63]
	ds_read_b128 v[82:85], v81 offset:34880
	ds_read_b128 v[86:89], v81 offset:34912
	v_mul_f32_e64 v44, v44, v80
	v_mul_f32_e64 v45, v45, v80
	v_mul_f32_e64 v42, v42, v80
	v_mul_f32_e64 v43, v43, v80
	v_pk_mul_f32 v[40:41], v[40:41], v[80:81] op_sel_hi:[1,0]
	v_pk_mul_f32 v[38:39], v[38:39], v[80:81] op_sel_hi:[1,0]
	v_pk_mul_f32 v[36:37], v[36:37], v[80:81] op_sel_hi:[1,0]
	v_pk_mul_f32 v[34:35], v[34:35], v[80:81] op_sel_hi:[1,0]
	s_waitcnt lgkmcnt(1)
	v_mfma_f32_32x32x16_bf16 v[48:63], v[82:85], v[68:71], v[48:63]
	ds_read_b128 v[82:85], v81 offset:39424
	v_mul_f32_e64 v32, v32, v80
	v_mul_f32_e64 v33, v33, v80
	v_mul_f32_e64 v14, v14, v80
	v_mul_f32_e64 v15, v15, v80
	v_pk_mul_f32 v[12:13], v[12:13], v[80:81] op_sel_hi:[1,0]
	v_pk_mul_f32 v[10:11], v[10:11], v[80:81] op_sel_hi:[1,0]
	v_pk_mul_f32 v[8:9], v[8:9], v[80:81] op_sel_hi:[1,0]
	v_pk_mul_f32 v[6:7], v[6:7], v[80:81] op_sel_hi:[1,0]
	s_waitcnt lgkmcnt(1)
	v_mfma_f32_32x32x16_bf16 v[48:63], v[86:89], v[64:67], v[48:63]
	ds_read_b128 v[86:89], v81 offset:39456
	v_mul_f32_e64 v4, v4, v80
	v_mul_f32_e64 v5, v5, v80
	v_mul_f32_e64 v2, v2, v80
	v_mul_f32_e64 v3, v3, v80
	v_pk_mul_f32 v[0:1], v[0:1], v[80:81] op_sel_hi:[1,0]
	v_cmp_gt_i32_e32 vcc, s30, v146
	s_waitcnt lgkmcnt(1)
	v_mfma_f32_32x32x16_bf16 v[16:31], v[82:85], v[76:79], v[16:31]
	s_waitcnt lgkmcnt(0)
	v_mfma_f32_32x32x16_bf16 v[16:31], v[86:89], v[72:75], v[16:31]
	ds_read_b128 v[82:85], v81 offset:39488
	ds_read_b128 v[86:89], v81 offset:39520
	s_waitcnt lgkmcnt(1)
	v_mfma_f32_32x32x16_bf16 v[16:31], v[82:85], v[68:71], v[16:31]
	ds_read_b128 v[82:85], v81 offset:44032
	s_waitcnt lgkmcnt(1)
	v_mfma_f32_32x32x16_bf16 v[16:31], v[86:89], v[64:67], v[16:31]
	ds_read_b128 v[86:89], v81 offset:44064
	s_waitcnt lgkmcnt(1)
	v_mfma_f32_32x32x16_bf16 v[32:47], v[82:85], v[76:79], v[32:47]
	s_waitcnt lgkmcnt(0)
	v_mfma_f32_32x32x16_bf16 v[32:47], v[86:89], v[72:75], v[32:47]
	ds_read_b128 v[82:85], v81 offset:44096
	ds_read_b128 v[86:89], v81 offset:44128
	s_waitcnt lgkmcnt(1)
	v_mfma_f32_32x32x16_bf16 v[32:47], v[82:85], v[68:71], v[32:47]
	ds_read_b128 v[82:85], v81 offset:48640
	s_waitcnt lgkmcnt(1)
	v_mfma_f32_32x32x16_bf16 v[32:47], v[86:89], v[64:67], v[32:47]
	ds_read_b128 v[86:89], v81 offset:48672
	s_waitcnt lgkmcnt(1)
	v_mfma_f32_32x32x16_bf16 v[0:15], v[82:85], v[76:79], v[0:15]
	s_waitcnt lgkmcnt(0)
	v_mfma_f32_32x32x16_bf16 v[0:15], v[86:89], v[72:75], v[0:15]
	ds_read_b128 v[72:75], v81 offset:48704
	ds_read_b128 v[76:79], v81 offset:48736
	s_waitcnt lgkmcnt(1)
	v_mfma_f32_32x32x16_bf16 v[0:15], v[72:75], v[68:71], v[0:15]
	s_waitcnt lgkmcnt(0)
	v_mfma_f32_32x32x16_bf16 v[0:15], v[76:79], v[64:67], v[0:15]
	s_and_saveexec_b64 s[0:1], vcc
	s_cbranch_execz .LBB0_195
; #define LAS __attribute__((address_space(3)))
; template <bool P2>
; DI void ml_pass(LAS unsigned char* lds, const bf16_t* PROJ, const float* GATES, float* STATE, float* SC, bf16_t* YM,
;                 const float* convw, const float* convb, const float* ogain, int G, int bid) {
;     ...
;             if (tid < 128) { float s = 0.f;
; #pragma unroll
;                 for (int q8 = 0; q8 < 8; ++q8) { const u32x4 kv = *(const LAS u32x4*)(Kt + tid * 72 + 8 * q8); s += (bflo(kv.x) + bfhi(kv.x)) + (bflo(kv.y) + bfhi(kv.y)) + (bflo(kv.z) + bfhi(kv.z)) + (bflo(kv.w) + bfhi(kv.w)); }
;                 ns[tid] = decay * ns[tid] + s; }
	v_mul_lo_u32 v64, v146, s25
	v_add_u32_e32 v81, 0, v64
	ds_read_b128 v[64:67], v81 offset:34816
	ds_read_b128 v[68:71], v81 offset:34832
	ds_read_b128 v[72:75], v81 offset:34848
	ds_read_b128 v[76:79], v81 offset:34864
	s_waitcnt lgkmcnt(3)
	v_lshlrev_b32_e32 v82, 16, v64
	s_waitcnt lgkmcnt(2)
	v_lshlrev_b32_e32 v83, 16, v68
	v_and_b32_e32 v85, 0xffff0000, v68
	v_and_b32_e32 v84, 0xffff0000, v64
	v_pk_add_f32 v[82:83], v[82:83], v[84:85]
	v_lshlrev_b32_e32 v85, 16, v69
	v_lshlrev_b32_e32 v84, 16, v65
	v_and_b32_e32 v69, 0xffff0000, v69
	v_and_b32_e32 v68, 0xffff0000, v65
	v_pk_add_f32 v[64:65], v[84:85], v[68:69]
	v_lshlrev_b32_e32 v69, 16, v70
	v_pk_add_f32 v[64:65], v[82:83], v[64:65]
	v_lshlrev_b32_e32 v68, 16, v66
	v_and_b32_e32 v83, 0xffff0000, v70
	v_and_b32_e32 v82, 0xffff0000, v66
	v_pk_add_f32 v[68:69], v[68:69], v[82:83]
	v_and_b32_e32 v70, 0xffff0000, v67
	v_pk_add_f32 v[64:65], v[68:69], v[64:65]
	v_lshlrev_b32_e32 v69, 16, v71
	v_lshlrev_b32_e32 v68, 16, v67
	v_and_b32_e32 v71, 0xffff0000, v71
	v_pk_add_f32 v[66:67], v[68:69], v[70:71]
	s_waitcnt lgkmcnt(1)
	v_and_b32_e32 v71, 0xffff0000, v75
	v_pk_add_f32 v[64:65], v[66:67], v[64:65]
	v_and_b32_e32 v67, 0xffff0000, v73
	v_add_f32_e32 v64, 0, v64
	v_add_f32_e32 v68, v64, v65
	v_lshlrev_b32_e32 v65, 16, v73
	v_lshlrev_b32_e32 v64, 16, v72
	v_and_b32_e32 v66, 0xffff0000, v72
	v_pk_add_f32 v[64:65], v[64:65], v[66:67]
	v_lshlrev_b32_e32 v67, 16, v75
	v_lshlrev_b32_e32 v66, 16, v74
	v_and_b32_e32 v70, 0xffff0000, v74
	v_pk_add_f32 v[64:65], v[64:65], v[64:65] op_sel:[0,1] op_sel_hi:[1,0]
	v_pk_add_f32 v[70:71], v[66:67], v[70:71]
	s_waitcnt lgkmcnt(0)
	v_lshlrev_b32_e32 v82, 16, v78
	v_pk_add_f32 v[72:73], v[70:71], v[64:65]
	v_lshlrev_b32_e32 v64, 16, v76
	v_and_b32_e32 v65, 0xffff0000, v76
	v_add_f32_e32 v74, v64, v65
	v_lshlrev_b32_e32 v64, 16, v77
	v_and_b32_e32 v65, 0xffff0000, v77
	v_add_f32_e32 v76, v64, v65
	ds_read_b128 v[64:67], v81 offset:34880
	s_waitcnt lgkmcnt(0)
	v_lshlrev_b32_e32 v75, 16, v65
	v_and_b32_e32 v77, 0xffff0000, v65
	v_lshlrev_b32_e32 v83, 16, v64
	v_and_b32_e32 v65, 0xffff0000, v64
	v_and_b32_e32 v64, 0xffff0000, v78
	v_pk_add_f32 v[64:65], v[82:83], v[64:65]
	v_pk_add_f32 v[74:75], v[74:75], v[76:77]
	v_lshlrev_b32_e32 v69, 16, v67
	v_pk_add_f32 v[64:65], v[64:65], v[74:75]
	v_pk_mov_b32 v[74:75], v[78:79], v[66:67] op_sel:[1,0]
	v_and_b32_e32 v84, 0xffff0000, v67
	v_lshlrev_b32_e32 v67, 16, v66
	v_lshlrev_b32_e32 v66, 16, v79
	v_and_b32_e32 v75, 0xffff0000, v75
	v_and_b32_e32 v74, 0xffff0000, v74
	v_pk_add_f32 v[66:67], v[66:67], v[74:75]
	s_nop 0
	v_pk_add_f32 v[64:65], v[66:67], v[64:65]
	v_pk_add_f32 v[66:67], v[70:71], v[72:73] op_sel:[1,0] op_sel_hi:[0,1]
	v_mov_b32_e32 v67, v84
	v_pk_add_f32 v[66:67], v[68:69], v[66:67]
	s_nop 0
	v_pk_add_f32 v[64:65], v[66:67], v[64:65]
	ds_read_b128 v[66:69], v81 offset:34896
	v_pk_add_f32 v[64:65], v[64:65], v[64:65] op_sel:[0,1] op_sel_hi:[1,0]
	s_waitcnt lgkmcnt(0)
	v_lshlrev_b32_e32 v71, 16, v67
	v_lshlrev_b32_e32 v70, 16, v66
	v_and_b32_e32 v67, 0xffff0000, v67
	v_and_b32_e32 v66, 0xffff0000, v66
	v_pk_add_f32 v[66:67], v[70:71], v[66:67]
	v_lshlrev_b32_e32 v71, 16, v69
	v_lshlrev_b32_e32 v70, 16, v68
	v_and_b32_e32 v69, 0xffff0000, v69
	v_and_b32_e32 v68, 0xffff0000, v68
	v_pk_add_f32 v[66:67], v[66:67], v[66:67] op_sel:[0,1] op_sel_hi:[1,0]
	v_pk_add_f32 v[74:75], v[70:71], v[68:69]
	s_nop 0
	v_pk_add_f32 v[76:77], v[74:75], v[66:67]
	ds_read_b128 v[66:69], v81 offset:34912
	s_waitcnt lgkmcnt(0)
	v_lshlrev_b32_e32 v70, 16, v66
	v_and_b32_e32 v66, 0xffff0000, v66
	v_add_f32_e32 v66, v70, v66
	v_lshlrev_b32_e32 v70, 16, v67
	v_and_b32_e32 v67, 0xffff0000, v67
	v_add_f32_e32 v78, v70, v67
	ds_read_b128 v[70:73], v81 offset:34928
	v_lshlrev_b32_e32 v82, 16, v68
	s_waitcnt lgkmcnt(0)
	v_lshlrev_b32_e32 v67, 16, v71
	v_and_b32_e32 v79, 0xffff0000, v71
	v_lshlrev_b32_e32 v83, 16, v70
	v_and_b32_e32 v71, 0xffff0000, v70
	v_and_b32_e32 v70, 0xffff0000, v68
	v_pk_add_f32 v[70:71], v[82:83], v[70:71]
	v_pk_add_f32 v[66:67], v[66:67], v[78:79]
	v_lshlrev_b32_e32 v81, 16, v73
	v_pk_add_f32 v[66:67], v[70:71], v[66:67]
	v_pk_mov_b32 v[70:71], v[68:69], v[72:73] op_sel:[1,0]
	v_and_b32_e32 v84, 0xffff0000, v73
	v_lshlrev_b32_e32 v73, 16, v72
	v_lshlrev_b32_e32 v72, 16, v69
	v_and_b32_e32 v69, 0xffff0000, v71
	v_and_b32_e32 v68, 0xffff0000, v70
	v_pk_add_f32 v[68:69], v[72:73], v[68:69]
	v_mov_b32_e32 v65, v81
	v_pk_add_f32 v[66:67], v[68:69], v[66:67]
	v_pk_add_f32 v[68:69], v[74:75], v[76:77] op_sel:[1,0] op_sel_hi:[0,1]
	v_mov_b32_e32 v69, v84
	v_pk_add_f32 v[64:65], v[64:65], v[68:69]
	s_nop 0
	v_pk_add_f32 v[64:65], v[64:65], v[66:67]
	s_nop 0
	v_add_f32_e32 v64, v64, v65
	v_lshl_add_u32 v65, v146, 2, 0
	v_add_u32_e32 v65, 0x20800, v65
	ds_read_b32 v66, v65
	s_waitcnt lgkmcnt(0)
	v_fmac_f32_e32 v64, v80, v66
	ds_write_b32 v65, v64
	s_branch .LBB0_195
